# GEMM K-loops: LDS-DMA destination (m0) and fragment read bases written directly as wave-offset + constant (27 SALU removed per 4 loops)
# speedup vs baseline: 1.0054x; 1.0022x over previous
; #define PG8_STAGE(bufoff, gbase, voff) do { _Pragma("unroll") for (int _i = 0; _i < 2; ++_i) \
;         __builtin_amdgcn_global_load_lds((const unsigned*)((const char*)(gbase) + (voff)[_i]), (PG8_LAS unsigned*)(lds + (bufoff) + ldsw + _i * 8192), 16, 0, 0); } while (0)
; #define PG8_LDA(dst, b, h) do { _Pragma("unroll") for (int m = 0; m < 4; ++m) _Pragma("unroll") for (int k = 0; k < 2; ++k) dst[m][k] = *(const PG8_LAS bf16x8*)(lds + PG8_SA(b, h) + aoff + m * 2048 + k * 1024); } while (0)
; #define PG8_LDB(dst, b, h) do { _Pragma("unroll") for (int n = 0; n < 2; ++n) _Pragma("unroll") for (int k = 0; k < 2; ++k) dst[n][k] = *(const PG8_LAS bf16x8*)(lds + PG8_SB(b, h) + boff + n * 2048 + k * 1024); } while (0)
; #define PG8_WAIT_V(n) asm volatile("s_waitcnt vmcnt(" #n ")" ::: "memory")
; #define PG8_WAIT_L(n) asm volatile("s_waitcnt lgkmcnt(" #n ")" ::: "memory")
; #define PG8_BAR __builtin_amdgcn_s_barrier()
; #define PG8_SCHED __builtin_amdgcn_sched_barrier(0)
; template <class Epi, class Sched>
; __device__ __forceinline__ void gemm_phase(PG8_LAS unsigned char* lds, const Gemm g, const Sched& S, const Epi& E) {
;     ...
;         const bool has_next = S.next(ui + 1, nxt);
;         const char* nA = has_next ? (const char*)g.A + (size_t)nxt.pm * tstep : cA; const char* nB = has_next ? (const char*)g.Bt + (size_t)nxt.pn * tstep : cB;
;         for (int t = 0; t < nt; t += 2) {
;             const bool last = (t == nt - 2);
;             const char* a1 = cA + (size_t)(t + 1) * kstep;
;             const char* a2 = last ? nA : cA + (size_t)(t + 2) * kstep; const char* b2 = last ? nB : cB + (size_t)(t + 2) * kstep;
;             const char* a3 = a2 + kstep; const char* b3 = b2 + kstep;
;             if (last && has_next) S.a_ready(nxt);
;             PG8_LDB(B0, 0, 0); PG8_SCHED; PG8_LDA(At, 0, 0); PG8_STAGE(PG8_SA(1, 1), a1 + hstep, voffA);
;             PG8_WAIT_L(8); PG8_BAR; PG8_WAIT_L(0); PG8_MMA(0, 0, At, B0); PG8_BAR; PG8_SCHED;
;             PG8_LDB(B1, 0, 1); PG8_STAGE(PG8_SB(0, 0), b2, voffB);
;             PG8_BAR; PG8_WAIT_L(0); PG8_MMA(0, 1, At, B1); PG8_BAR;
;             PG8_LDA(At, 0, 1); PG8_STAGE(PG8_SA(0, 0), a2, voffA);
;             PG8_BAR; PG8_WAIT_L(0); PG8_MMA(1, 0, At, B0); PG8_BAR; PG8_SCHED;
;             PG8_STAGE(PG8_SB(0, 1), b2 + hstep, voffB);
;             PG8_WAIT_V(6); PG8_BAR; PG8_MMA(1, 1, At, B1); PG8_BAR;
.LBB0_96:
	s_add_u32 s10, s8, 0x100
	s_addc_u32 s11, s9, 0
	v_add_u32_e32 v154, 0x10000, v139
	ds_read_b128 v[142:145], v154
	ds_read_b128 v[146:149], v154 offset:1024
	ds_read_b128 v[150:153], v154 offset:2048
	ds_read_b128 v[154:157], v154 offset:3072
	s_cmp_eq_u32 s45, 40
	s_cselect_b32 s15, s1, s11
	s_cselect_b32 s14, s0, s10
	s_cselect_b32 s13, s5, s44
	s_cselect_b32 s12, s4, s43
	s_add_i32 m0, s20, 0xc000
	ds_read_b128 v[158:161], v141
	ds_read_b128 v[162:165], v141 offset:1024
	ds_read_b128 v[166:169], v141 offset:2048
	ds_read_b128 v[170:173], v141 offset:3072
	ds_read_b128 v[178:181], v141 offset:4096
	ds_read_b128 v[182:185], v141 offset:5120
	ds_read_b128 v[186:189], v141 offset:6144
	ds_read_b128 v[190:193], v141 offset:7168
	global_load_lds_dwordx4 v134, s[8:9]
	s_add_i32 m0, s20, 0xe000
	s_nop 0
	global_load_lds_dwordx4 v136, s[8:9]
	s_waitcnt lgkmcnt(8)
	s_barrier
	s_waitcnt lgkmcnt(0)
	v_mfma_f32_16x16x32_bf16 v[124:127], v[142:145], v[158:161], v[124:127]
	v_mfma_f32_16x16x32_bf16 v[120:123], v[150:153], v[158:161], v[120:123]
	v_mfma_f32_16x16x32_bf16 v[116:119], v[142:145], v[166:169], v[116:119]
	v_mfma_f32_16x16x32_bf16 v[112:115], v[150:153], v[166:169], v[112:115]
	v_mfma_f32_16x16x32_bf16 v[100:103], v[142:145], v[178:181], v[100:103]
	v_mfma_f32_16x16x32_bf16 v[96:99], v[150:153], v[178:181], v[96:99]
	v_mfma_f32_16x16x32_bf16 v[84:87], v[142:145], v[186:189], v[84:87]
	v_mfma_f32_16x16x32_bf16 v[80:83], v[150:153], v[186:189], v[80:83]
	v_mfma_f32_16x16x32_bf16 v[124:127], v[146:149], v[162:165], v[124:127]
	v_mfma_f32_16x16x32_bf16 v[120:123], v[154:157], v[162:165], v[120:123]
	v_mfma_f32_16x16x32_bf16 v[116:119], v[146:149], v[170:173], v[116:119]
	v_mfma_f32_16x16x32_bf16 v[112:115], v[154:157], v[170:173], v[112:115]
	v_mfma_f32_16x16x32_bf16 v[100:103], v[146:149], v[182:185], v[100:103]
	v_mfma_f32_16x16x32_bf16 v[96:99], v[154:157], v[182:185], v[96:99]
	v_mfma_f32_16x16x32_bf16 v[84:87], v[146:149], v[190:193], v[84:87]
	v_mfma_f32_16x16x32_bf16 v[80:83], v[154:157], v[190:193], v[80:83]
	s_barrier
	s_add_i32 s47, 0, 0x14000
	v_add_u32_e32 v174, 0x14000, v139
	ds_read_b128 v[194:197], v174
	ds_read_b128 v[198:201], v174 offset:1024
	ds_read_b128 v[202:205], v174 offset:2048
	ds_read_b128 v[206:209], v174 offset:3072
	s_add_u32 s98, s12, 0x80
	s_addc_u32 s99, s13, 0
	s_add_i32 m0, s18, 0x10000
	s_nop 0
	global_load_lds_dwordx4 v176, s[12:13]
	s_add_i32 m0, s18, 0x12000
	s_nop 0
	global_load_lds_dwordx4 v128, s[12:13]
	s_barrier
	s_waitcnt lgkmcnt(0)
	v_mfma_f32_16x16x32_bf16 v[108:111], v[194:197], v[158:161], v[108:111]
	v_mfma_f32_16x16x32_bf16 v[104:107], v[202:205], v[158:161], v[104:107]
	v_mfma_f32_16x16x32_bf16 v[92:95], v[194:197], v[166:169], v[92:95]
	v_mfma_f32_16x16x32_bf16 v[88:91], v[202:205], v[166:169], v[88:91]
	v_mfma_f32_16x16x32_bf16 v[76:79], v[194:197], v[178:181], v[76:79]
	v_mfma_f32_16x16x32_bf16 v[72:75], v[202:205], v[178:181], v[72:75]
	v_mfma_f32_16x16x32_bf16 v[68:71], v[194:197], v[186:189], v[68:71]
	v_mfma_f32_16x16x32_bf16 v[64:67], v[202:205], v[186:189], v[64:67]
	v_mfma_f32_16x16x32_bf16 v[108:111], v[198:201], v[162:165], v[108:111]
	v_mfma_f32_16x16x32_bf16 v[104:107], v[206:209], v[162:165], v[104:107]
	v_mfma_f32_16x16x32_bf16 v[92:95], v[198:201], v[170:173], v[92:95]
	v_mfma_f32_16x16x32_bf16 v[88:91], v[206:209], v[170:173], v[88:91]
	v_mfma_f32_16x16x32_bf16 v[76:79], v[198:201], v[182:185], v[76:79]
	v_mfma_f32_16x16x32_bf16 v[72:75], v[206:209], v[182:185], v[72:75]
	v_mfma_f32_16x16x32_bf16 v[68:71], v[198:201], v[190:193], v[68:71]
	v_mfma_f32_16x16x32_bf16 v[64:67], v[206:209], v[190:193], v[64:67]
	s_mov_b32 m0, s20
	s_add_u32 s100, s14, 0x80
	s_addc_u32 s101, s15, 0
	s_barrier
	ds_read_b128 v[158:161], v141 offset:16384
	ds_read_b128 v[162:165], v141 offset:17408
	ds_read_b128 v[166:169], v141 offset:18432
	ds_read_b128 v[170:173], v141 offset:19456
	ds_read_b128 v[178:181], v141 offset:20480
	ds_read_b128 v[182:185], v141 offset:21504
	ds_read_b128 v[186:189], v141 offset:22528
	ds_read_b128 v[190:193], v141 offset:23552
	global_load_lds_dwordx4 v132, s[14:15]
	s_mov_b32 m0, s21
	s_nop 0
	global_load_lds_dwordx4 v130, s[14:15]
	s_barrier
	s_waitcnt lgkmcnt(0)
	v_mfma_f32_16x16x32_bf16 v[60:63], v[142:145], v[158:161], v[60:63]
	v_mfma_f32_16x16x32_bf16 v[56:59], v[150:153], v[158:161], v[56:59]
	v_mfma_f32_16x16x32_bf16 v[52:55], v[142:145], v[166:169], v[52:55]
	v_mfma_f32_16x16x32_bf16 v[48:51], v[150:153], v[166:169], v[48:51]
	v_mfma_f32_16x16x32_bf16 v[36:39], v[142:145], v[178:181], v[36:39]
	v_mfma_f32_16x16x32_bf16 v[32:35], v[150:153], v[178:181], v[32:35]
	v_mfma_f32_16x16x32_bf16 v[20:23], v[142:145], v[186:189], v[20:23]
	v_mfma_f32_16x16x32_bf16 v[16:19], v[150:153], v[186:189], v[16:19]
	v_mfma_f32_16x16x32_bf16 v[60:63], v[146:149], v[162:165], v[60:63]
	v_mfma_f32_16x16x32_bf16 v[56:59], v[154:157], v[162:165], v[56:59]
	v_mfma_f32_16x16x32_bf16 v[52:55], v[146:149], v[170:173], v[52:55]
	v_mfma_f32_16x16x32_bf16 v[48:51], v[154:157], v[170:173], v[48:51]
	v_mfma_f32_16x16x32_bf16 v[36:39], v[146:149], v[182:185], v[36:39]
	v_mfma_f32_16x16x32_bf16 v[32:35], v[154:157], v[182:185], v[32:35]
	v_mfma_f32_16x16x32_bf16 v[20:23], v[146:149], v[190:193], v[20:23]
	v_mfma_f32_16x16x32_bf16 v[16:19], v[154:157], v[190:193], v[16:19]
	s_barrier
	s_add_u32 s8, s12, 0xb0000
	s_addc_u32 s9, s13, 0
	s_add_i32 m0, s18, 0x14000
	s_nop 0
	global_load_lds_dwordx4 v176, s[8:9]
	s_add_i32 m0, s18, 0x16000
	s_nop 0
	global_load_lds_dwordx4 v128, s[8:9]
	s_waitcnt vmcnt(6)
	s_barrier
; #define PG8_STAGE(bufoff, gbase, voff) do { _Pragma("unroll") for (int _i = 0; _i < 2; ++_i) \
;         __builtin_amdgcn_global_load_lds((const unsigned*)((const char*)(gbase) + (voff)[_i]), (PG8_LAS unsigned*)(lds + (bufoff) + ldsw + _i * 8192), 16, 0, 0); } while (0)
; #define PG8_LDA(dst, b, h) do { _Pragma("unroll") for (int m = 0; m < 4; ++m) _Pragma("unroll") for (int k = 0; k < 2; ++k) dst[m][k] = *(const PG8_LAS bf16x8*)(lds + PG8_SA(b, h) + aoff + m * 2048 + k * 1024); } while (0)
; #define PG8_LDB(dst, b, h) do { _Pragma("unroll") for (int n = 0; n < 2; ++n) _Pragma("unroll") for (int k = 0; k < 2; ++k) dst[n][k] = *(const PG8_LAS bf16x8*)(lds + PG8_SB(b, h) + boff + n * 2048 + k * 1024); } while (0)
; #define PG8_MMA(ai, bj, At, Bt) do { __builtin_amdgcn_s_setprio(1); _Pragma("unroll") for (int m = 0; m < 4; ++m) _Pragma("unroll") for (int n = 0; n < 2; ++n) _Pragma("unroll") for (int k = 0; k < 2; ++k) \
;         acc[ai][bj][m][n] = __builtin_amdgcn_mfma_f32_16x16x32_bf16(Bt[n][k], At[m][k], acc[ai][bj][m][n], 0, 0, 0); __builtin_amdgcn_s_setprio(0); } while (0)
; #define PG8_WAIT_V(n) asm volatile("s_waitcnt vmcnt(" #n ")" ::: "memory")
; #define PG8_WAIT_L(n) asm volatile("s_waitcnt lgkmcnt(" #n ")" ::: "memory")
; #define PG8_BAR __builtin_amdgcn_s_barrier()
; #define PG8_SCHED __builtin_amdgcn_sched_barrier(0)
; template <class Epi, class Sched>
; __device__ __forceinline__ void gemm_phase(PG8_LAS unsigned char* lds, const Gemm g, const Sched& S, const Epi& E) {
;     ...
;             PG8_WAIT_V(6); PG8_BAR; PG8_MMA(1, 1, At, B1); PG8_BAR;
;             PG8_LDB(B0, 1, 0); PG8_SCHED; PG8_LDA(At, 1, 0); PG8_STAGE(PG8_SA(0, 1), a2 + hstep, voffA);
;             PG8_WAIT_L(8); PG8_BAR; PG8_WAIT_L(0); PG8_MMA(0, 0, At, B0); PG8_BAR; PG8_SCHED;
;             PG8_LDB(B1, 1, 1); PG8_STAGE(PG8_SB(1, 0), b3, voffB);
;             PG8_BAR; PG8_WAIT_L(0); PG8_MMA(0, 1, At, B1); PG8_BAR;
;             PG8_LDA(At, 1, 1); PG8_STAGE(PG8_SA(1, 0), a3, voffA);
	v_mfma_f32_16x16x32_bf16 v[44:47], v[194:197], v[158:161], v[44:47]
	v_mfma_f32_16x16x32_bf16 v[40:43], v[202:205], v[158:161], v[40:43]
	v_mfma_f32_16x16x32_bf16 v[28:31], v[194:197], v[166:169], v[28:31]
	v_mfma_f32_16x16x32_bf16 v[24:27], v[202:205], v[166:169], v[24:27]
	v_mfma_f32_16x16x32_bf16 v[12:15], v[194:197], v[178:181], v[12:15]
	v_mfma_f32_16x16x32_bf16 v[8:11], v[202:205], v[178:181], v[8:11]
	v_mfma_f32_16x16x32_bf16 v[4:7], v[194:197], v[186:189], v[4:7]
	v_mfma_f32_16x16x32_bf16 v[0:3], v[202:205], v[186:189], v[0:3]
	v_mfma_f32_16x16x32_bf16 v[44:47], v[198:201], v[162:165], v[44:47]
	v_mfma_f32_16x16x32_bf16 v[40:43], v[206:209], v[162:165], v[40:43]
	v_mfma_f32_16x16x32_bf16 v[28:31], v[198:201], v[170:173], v[28:31]
	v_mfma_f32_16x16x32_bf16 v[24:27], v[206:209], v[170:173], v[24:27]
	v_mfma_f32_16x16x32_bf16 v[12:15], v[198:201], v[182:185], v[12:15]
	v_mfma_f32_16x16x32_bf16 v[8:11], v[206:209], v[182:185], v[8:11]
	v_mfma_f32_16x16x32_bf16 v[4:7], v[198:201], v[190:193], v[4:7]
	v_mfma_f32_16x16x32_bf16 v[0:3], v[206:209], v[190:193], v[0:3]
	s_add_i32 s46, 0, 0x18000
	v_add_u32_e32 v154, 0x18000, v139
	s_barrier
	ds_read_b128 v[142:145], v154
	ds_read_b128 v[146:149], v154 offset:1024
	ds_read_b128 v[150:153], v154 offset:2048
	ds_read_b128 v[154:157], v154 offset:3072
	s_add_u32 s8, s14, 0xb0000
	s_addc_u32 s9, s15, 0
	s_mov_b32 m0, s22
	ds_read_b128 v[158:161], v141 offset:32768
	ds_read_b128 v[162:165], v141 offset:33792
	ds_read_b128 v[166:169], v141 offset:34816
	ds_read_b128 v[170:173], v141 offset:35840
	ds_read_b128 v[178:181], v141 offset:36864
	ds_read_b128 v[182:185], v141 offset:37888
	ds_read_b128 v[186:189], v141 offset:38912
	ds_read_b128 v[190:193], v141 offset:39936
	global_load_lds_dwordx4 v132, s[8:9]
	s_mov_b32 m0, s23
	s_nop 0
	global_load_lds_dwordx4 v130, s[8:9]
	s_waitcnt lgkmcnt(8)
	s_barrier
	s_waitcnt lgkmcnt(0)
	v_mfma_f32_16x16x32_bf16 v[124:127], v[142:145], v[158:161], v[124:127]
	v_mfma_f32_16x16x32_bf16 v[120:123], v[150:153], v[158:161], v[120:123]
	v_mfma_f32_16x16x32_bf16 v[116:119], v[142:145], v[166:169], v[116:119]
	v_mfma_f32_16x16x32_bf16 v[112:115], v[150:153], v[166:169], v[112:115]
	v_mfma_f32_16x16x32_bf16 v[100:103], v[142:145], v[178:181], v[100:103]
	v_mfma_f32_16x16x32_bf16 v[96:99], v[150:153], v[178:181], v[96:99]
	v_mfma_f32_16x16x32_bf16 v[84:87], v[142:145], v[186:189], v[84:87]
	v_mfma_f32_16x16x32_bf16 v[80:83], v[150:153], v[186:189], v[80:83]
	v_mfma_f32_16x16x32_bf16 v[124:127], v[146:149], v[162:165], v[124:127]
	v_mfma_f32_16x16x32_bf16 v[120:123], v[154:157], v[162:165], v[120:123]
	v_mfma_f32_16x16x32_bf16 v[116:119], v[146:149], v[170:173], v[116:119]
	v_mfma_f32_16x16x32_bf16 v[112:115], v[154:157], v[170:173], v[112:115]
	v_mfma_f32_16x16x32_bf16 v[100:103], v[146:149], v[182:185], v[100:103]
	v_mfma_f32_16x16x32_bf16 v[96:99], v[154:157], v[182:185], v[96:99]
	v_mfma_f32_16x16x32_bf16 v[84:87], v[146:149], v[190:193], v[84:87]
	v_mfma_f32_16x16x32_bf16 v[80:83], v[154:157], v[190:193], v[80:83]
	s_barrier
	v_add_u32_e32 v206, 0x1c000, v139
	s_add_i32 m0, s18, 0x18000
	ds_read_b128 v[194:197], v206
	ds_read_b128 v[198:201], v206 offset:1024
	ds_read_b128 v[202:205], v206 offset:2048
	ds_read_b128 v[206:209], v206 offset:3072
	global_load_lds_dwordx4 v176, s[98:99]
	s_add_i32 m0, s18, 0x1a000
	s_nop 0
	global_load_lds_dwordx4 v128, s[98:99]
	s_barrier
	s_waitcnt lgkmcnt(0)
	v_mfma_f32_16x16x32_bf16 v[108:111], v[194:197], v[158:161], v[108:111]
	v_mfma_f32_16x16x32_bf16 v[104:107], v[202:205], v[158:161], v[104:107]
	v_mfma_f32_16x16x32_bf16 v[92:95], v[194:197], v[166:169], v[92:95]
	v_mfma_f32_16x16x32_bf16 v[88:91], v[202:205], v[166:169], v[88:91]
	v_mfma_f32_16x16x32_bf16 v[76:79], v[194:197], v[178:181], v[76:79]
	v_mfma_f32_16x16x32_bf16 v[72:75], v[202:205], v[178:181], v[72:75]
	v_mfma_f32_16x16x32_bf16 v[68:71], v[194:197], v[186:189], v[68:71]
	v_mfma_f32_16x16x32_bf16 v[64:67], v[202:205], v[186:189], v[64:67]
	v_mfma_f32_16x16x32_bf16 v[108:111], v[198:201], v[162:165], v[108:111]
	v_mfma_f32_16x16x32_bf16 v[104:107], v[206:209], v[162:165], v[104:107]
	v_mfma_f32_16x16x32_bf16 v[92:95], v[198:201], v[170:173], v[92:95]
	v_mfma_f32_16x16x32_bf16 v[88:91], v[206:209], v[170:173], v[88:91]
	v_mfma_f32_16x16x32_bf16 v[76:79], v[198:201], v[182:185], v[76:79]
	v_mfma_f32_16x16x32_bf16 v[72:75], v[206:209], v[182:185], v[72:75]
	v_mfma_f32_16x16x32_bf16 v[68:71], v[198:201], v[190:193], v[68:71]
	v_mfma_f32_16x16x32_bf16 v[64:67], v[206:209], v[190:193], v[64:67]
	s_mov_b32 m0, s27
	s_barrier
	ds_read_b128 v[158:161], v141 offset:49152
	ds_read_b128 v[162:165], v141 offset:50176
	ds_read_b128 v[166:169], v141 offset:51200
	ds_read_b128 v[170:173], v141 offset:52224
	ds_read_b128 v[178:181], v141 offset:53248
	ds_read_b128 v[182:185], v141 offset:54272
	ds_read_b128 v[186:189], v141 offset:55296
	ds_read_b128 v[190:193], v141 offset:56320
	global_load_lds_dwordx4 v132, s[100:101]
	s_mov_b32 m0, s28
	s_nop 0
	global_load_lds_dwordx4 v130, s[100:101]
	s_barrier
	s_waitcnt lgkmcnt(0)
	v_mfma_f32_16x16x32_bf16 v[60:63], v[142:145], v[158:161], v[60:63]
	v_mfma_f32_16x16x32_bf16 v[56:59], v[150:153], v[158:161], v[56:59]
	v_mfma_f32_16x16x32_bf16 v[52:55], v[142:145], v[166:169], v[52:55]
	v_mfma_f32_16x16x32_bf16 v[48:51], v[150:153], v[166:169], v[48:51]
	v_mfma_f32_16x16x32_bf16 v[36:39], v[142:145], v[178:181], v[36:39]
	v_mfma_f32_16x16x32_bf16 v[32:35], v[150:153], v[178:181], v[32:35]
	v_mfma_f32_16x16x32_bf16 v[20:23], v[142:145], v[186:189], v[20:23]
	v_mfma_f32_16x16x32_bf16 v[16:19], v[150:153], v[186:189], v[16:19]
	v_mfma_f32_16x16x32_bf16 v[60:63], v[146:149], v[162:165], v[60:63]
	v_mfma_f32_16x16x32_bf16 v[56:59], v[154:157], v[162:165], v[56:59]
	v_mfma_f32_16x16x32_bf16 v[52:55], v[146:149], v[170:173], v[52:55]
	v_mfma_f32_16x16x32_bf16 v[48:51], v[154:157], v[170:173], v[48:51]
	v_mfma_f32_16x16x32_bf16 v[36:39], v[146:149], v[182:185], v[36:39]
	v_mfma_f32_16x16x32_bf16 v[32:35], v[154:157], v[182:185], v[32:35]
	v_mfma_f32_16x16x32_bf16 v[20:23], v[146:149], v[190:193], v[20:23]
	v_mfma_f32_16x16x32_bf16 v[16:19], v[154:157], v[190:193], v[16:19]
	s_barrier
; __device__ __forceinline__ unsigned cvtpk(float lo, float hi) { const f32x2 v = (f32x2){lo, hi}; const bf16v2 b = __builtin_convertvector(v, bf16v2); return __builtin_bit_cast(unsigned, b); }
; #define PG8_STAGE(bufoff, gbase, voff) do { _Pragma("unroll") for (int _i = 0; _i < 2; ++_i) \
;         __builtin_amdgcn_global_load_lds((const unsigned*)((const char*)(gbase) + (voff)[_i]), (PG8_LAS unsigned*)(lds + (bufoff) + ldsw + _i * 8192), 16, 0, 0); } while (0)
; #define PG8_LDA(dst, b, h) do { _Pragma("unroll") for (int m = 0; m < 4; ++m) _Pragma("unroll") for (int k = 0; k < 2; ++k) dst[m][k] = *(const PG8_LAS bf16x8*)(lds + PG8_SA(b, h) + aoff + m * 2048 + k * 1024); } while (0)
; #define PG8_MMA(ai, bj, At, Bt) do { __builtin_amdgcn_s_setprio(1); _Pragma("unroll") for (int m = 0; m < 4; ++m) _Pragma("unroll") for (int n = 0; n < 2; ++n) _Pragma("unroll") for (int k = 0; k < 2; ++k) \
;         acc[ai][bj][m][n] = __builtin_amdgcn_mfma_f32_16x16x32_bf16(Bt[n][k], At[m][k], acc[ai][bj][m][n], 0, 0, 0); __builtin_amdgcn_s_setprio(0); } while (0)
; #define PG8_BAR __builtin_amdgcn_s_barrier()
; template <class Epi, class Sched>
; __device__ __forceinline__ void gemm_phase(PG8_LAS unsigned char* lds, const Gemm g, const Sched& S, const Epi& E) {
;     ...
;             PG8_LDA(At, 1, 1); PG8_STAGE(PG8_SA(1, 0), a3, voffA);
;             PG8_BAR; PG8_WAIT_L(0); PG8_MMA(1, 0, At, B0); PG8_BAR; PG8_SCHED;
;             PG8_STAGE(PG8_SB(1, 1), b3 + hstep, voffB);
;             PG8_WAIT_V(6); PG8_BAR; PG8_MMA(1, 1, At, B1); PG8_BAR;
;         }
;         if constexpr (!Epi::AFTER_DRAIN) { E(acc, cur, wr, wc, fr, fq); S.done(cur); }
;     __device__ __forceinline__ void operator()(const f32x4 (&acc)[2][2][4][2], const pg8::Unit& u, int wr, int wc, int fr, int fq) const {
;         const int row0 = u.pm * 256 + wr * 64 + fr, col0 = u.pn * 256 + wc * 32 + 8 * fq;
; #pragma unroll
;         for (int ai = 0; ai < 2; ++ai)
; #pragma unroll
;             for (int m = 0; m < 4; ++m) { bf16_t* rowp = O + (size_t)(row0 + ai * 128 + m * 16) * ldc + col0;
; #pragma unroll
;                 for (int bj = 0; bj < 2; ++bj) { const f32x4 v0 = acc[ai][bj][m][0], v1 = acc[ai][bj][m][1];
;                     u32x4 w; w.x = cvtpk(v0[0], v0[1]); w.y = cvtpk(v0[2], v0[3]); w.z = cvtpk(v1[0], v1[1]); w.w = cvtpk(v1[2], v1[3]);
;                     *(u32x4*)(rowp + bj * 128) = w; } }
	s_add_u32 s8, s12, 0xb0080
	s_addc_u32 s9, s13, 0
	s_add_i32 m0, s18, 0x1c000
	s_nop 0
	global_load_lds_dwordx4 v176, s[8:9]
	s_add_i32 m0, s18, 0x1e000
	s_nop 0
	global_load_lds_dwordx4 v128, s[8:9]
	s_waitcnt vmcnt(6)
	s_barrier
	v_mfma_f32_16x16x32_bf16 v[44:47], v[194:197], v[158:161], v[44:47]
	v_mfma_f32_16x16x32_bf16 v[40:43], v[202:205], v[158:161], v[40:43]
	v_mfma_f32_16x16x32_bf16 v[28:31], v[194:197], v[166:169], v[28:31]
	v_mfma_f32_16x16x32_bf16 v[24:27], v[202:205], v[166:169], v[24:27]
	v_mfma_f32_16x16x32_bf16 v[12:15], v[194:197], v[178:181], v[12:15]
	v_mfma_f32_16x16x32_bf16 v[8:11], v[202:205], v[178:181], v[8:11]
	v_mfma_f32_16x16x32_bf16 v[4:7], v[194:197], v[186:189], v[4:7]
	v_mfma_f32_16x16x32_bf16 v[0:3], v[202:205], v[186:189], v[0:3]
	v_mfma_f32_16x16x32_bf16 v[44:47], v[198:201], v[162:165], v[44:47]
	v_mfma_f32_16x16x32_bf16 v[40:43], v[206:209], v[162:165], v[40:43]
	v_mfma_f32_16x16x32_bf16 v[28:31], v[198:201], v[170:173], v[28:31]
	v_mfma_f32_16x16x32_bf16 v[24:27], v[206:209], v[170:173], v[24:27]
	v_mfma_f32_16x16x32_bf16 v[12:15], v[198:201], v[182:185], v[12:15]
	v_mfma_f32_16x16x32_bf16 v[8:11], v[206:209], v[182:185], v[8:11]
	v_mfma_f32_16x16x32_bf16 v[4:7], v[198:201], v[190:193], v[4:7]
	v_mfma_f32_16x16x32_bf16 v[0:3], v[206:209], v[190:193], v[0:3]
	s_add_i32 s45, s45, 2
	s_add_u32 s43, s43, 0x100
	s_addc_u32 s44, s44, 0
	s_cmp_gt_u32 s45, 41
	s_mov_b64 s[8:9], s[10:11]
	s_barrier
	s_cbranch_scc0 .LBB0_96
	v_lshl_add_u32 v142, s29, 8, v138
	v_lshl_or_b32 v144, s34, 8, v140
	v_ashrrev_i32_e32 v143, 31, v142
	v_readlane_b32 s8, v253, 18
	v_cvt_pk_bf16_f32 v108, v108, v109
	v_cvt_pk_bf16_f32 v109, v110, v111
	v_cvt_pk_bf16_f32 v110, v104, v105
	v_or_b32_e32 v104, 16, v142
	v_cvt_pk_bf16_f32 v92, v92, v93
	v_cvt_pk_bf16_f32 v93, v94, v95
	v_cvt_pk_bf16_f32 v94, v88, v89
	v_or_b32_e32 v88, 32, v142
	v_cvt_pk_bf16_f32 v76, v76, v77
	v_cvt_pk_bf16_f32 v77, v78, v79
	v_cvt_pk_bf16_f32 v78, v72, v73
	v_or_b32_e32 v72, 48, v142
	v_ashrrev_i32_e32 v145, 31, v144
	v_lshlrev_b64 v[146:147], 11, v[142:143]
	v_readlane_b32 s9, v253, 19
	v_ashrrev_i32_e32 v105, 31, v104
	v_ashrrev_i32_e32 v89, 31, v88
	v_ashrrev_i32_e32 v73, 31, v72
	v_lshl_add_u64 v[146:147], s[8:9], 0, v[146:147]
	v_lshlrev_b64 v[144:145], 1, v[144:145]
	v_lshlrev_b64 v[104:105], 11, v[104:105]
	v_lshlrev_b64 v[88:89], 11, v[88:89]
	v_lshlrev_b64 v[72:73], 11, v[72:73]
	v_lshl_add_u64 v[146:147], v[146:147], 0, v[144:145]
	v_lshl_add_u64 v[104:105], s[8:9], 0, v[104:105]
	v_lshl_add_u64 v[88:89], s[8:9], 0, v[88:89]
	v_lshl_add_u64 v[72:73], s[8:9], 0, v[72:73]
	s_mov_b64 s[8:9], 0x40000
	v_cvt_pk_bf16_f32 v68, v68, v69
	v_cvt_pk_bf16_f32 v69, v70, v71
	v_cvt_pk_bf16_f32 v70, v64, v65
	v_lshl_add_u64 v[64:65], v[146:147], 0, s[8:9]
	v_cvt_pk_bf16_f32 v60, v60, v61
	v_cvt_pk_bf16_f32 v61, v62, v63
	v_cvt_pk_bf16_f32 v62, v56, v57
	v_add_co_u32_e32 v56, vcc, s2, v146
	v_cvt_pk_bf16_f32 v44, v44, v45
	v_cvt_pk_bf16_f32 v45, v46, v47
	v_cvt_pk_bf16_f32 v46, v40, v41
	v_cvt_pk_bf16_f32 v47, v42, v43
	s_mov_b64 s[8:9], 0x48000
	v_addc_co_u32_e32 v57, vcc, 0, v147, vcc
	global_store_dwordx4 v[64:65], v[44:47], off offset:256
	v_cvt_pk_bf16_f32 v28, v28, v29
	v_cvt_pk_bf16_f32 v29, v30, v31
	v_lshl_add_u64 v[44:45], v[146:147], 0, s[8:9]
	s_mov_b32 s8, 0x48000
	v_add_co_u32_e32 v46, vcc, s8, v146
	v_cvt_pk_bf16_f32 v30, v24, v25
	v_cvt_pk_bf16_f32 v31, v26, v27
	s_mov_b64 s[8:9], 0x50000
	v_addc_co_u32_e32 v47, vcc, 0, v147, vcc
	global_store_dwordx4 v[44:45], v[28:31], off offset:256
	v_cvt_pk_bf16_f32 v12, v12, v13
	v_cvt_pk_bf16_f32 v13, v14, v15
	v_lshl_add_u64 v[28:29], v[146:147], 0, s[8:9]
	s_mov_b32 s8, 0x50000
	v_add_co_u32_e32 v30, vcc, s8, v146
	v_cvt_pk_bf16_f32 v14, v8, v9
	v_cvt_pk_bf16_f32 v15, v10, v11
	s_mov_b64 s[8:9], 0x58000
	v_cvt_pk_bf16_f32 v111, v106, v107
	v_addc_co_u32_e32 v31, vcc, 0, v147, vcc
	global_store_dwordx4 v[28:29], v[12:15], off offset:256
	global_store_dwordx4 v[146:147], v[108:111], off offset:256
	v_cvt_pk_bf16_f32 v95, v90, v91
	v_lshl_add_u64 v[12:13], v[146:147], 0, s[8:9]
	s_mov_b32 s8, 0x58000
	v_lshl_add_u64 v[108:109], v[104:105], 0, v[144:145]
	v_add_co_u32_e32 v14, vcc, s8, v146
	global_store_dwordx4 v[108:109], v[92:95], off offset:256
	v_cvt_pk_bf16_f32 v79, v74, v75
	v_addc_co_u32_e32 v15, vcc, 0, v147, vcc
	v_lshl_add_u64 v[92:93], v[88:89], 0, v[144:145]
	v_cvt_pk_bf16_f32 v124, v124, v125
	v_cvt_pk_bf16_f32 v125, v126, v127
	v_cvt_pk_bf16_f32 v126, v120, v121
	v_cvt_pk_bf16_f32 v127, v122, v123
	v_cvt_pk_bf16_f32 v104, v116, v117
	v_cvt_pk_bf16_f32 v105, v118, v119
	v_cvt_pk_bf16_f32 v106, v112, v113
	v_cvt_pk_bf16_f32 v107, v114, v115
	v_cvt_pk_bf16_f32 v88, v100, v101
	v_cvt_pk_bf16_f32 v89, v102, v103
	v_cvt_pk_bf16_f32 v90, v96, v97
	v_cvt_pk_bf16_f32 v91, v98, v99
	global_store_dwordx4 v[92:93], v[76:79], off offset:256
	v_cvt_pk_bf16_f32 v74, v80, v81
	v_cvt_pk_bf16_f32 v75, v82, v83
	v_lshl_add_u64 v[76:77], v[72:73], 0, v[144:145]
	v_cvt_pk_bf16_f32 v72, v84, v85
	v_cvt_pk_bf16_f32 v73, v86, v87
	v_cvt_pk_bf16_f32 v71, v66, v67
	v_cvt_pk_bf16_f32 v63, v58, v59
	v_cvt_pk_bf16_f32 v40, v52, v53
	v_cvt_pk_bf16_f32 v41, v54, v55
	v_cvt_pk_bf16_f32 v42, v48, v49
	v_cvt_pk_bf16_f32 v43, v50, v51
	v_cvt_pk_bf16_f32 v24, v36, v37
	v_cvt_pk_bf16_f32 v25, v38, v39
	v_cvt_pk_bf16_f32 v26, v32, v33
	v_cvt_pk_bf16_f32 v27, v34, v35
	v_cvt_pk_bf16_f32 v8, v20, v21
	v_cvt_pk_bf16_f32 v9, v22, v23
	v_cvt_pk_bf16_f32 v10, v16, v17
	v_cvt_pk_bf16_f32 v11, v18, v19
	v_cvt_pk_bf16_f32 v4, v4, v5
	v_cvt_pk_bf16_f32 v5, v6, v7
	v_cvt_pk_bf16_f32 v6, v0, v1
	v_cvt_pk_bf16_f32 v7, v2, v3
	s_and_b64 vcc, exec, s[38:39]
	s_mov_b32 s34, s40
	s_mov_b32 s29, s41
	s_mov_b64 s[10:11], s[4:5]
	s_mov_b64 s[8:9], s[0:1]
	global_store_dwordx4 v[146:147], v[124:127], off
	global_store_dwordx4 v[108:109], v[104:107], off
	global_store_dwordx4 v[92:93], v[88:91], off
	global_store_dwordx4 v[76:77], v[72:75], off
	global_store_dwordx4 v[76:77], v[68:71], off offset:256
	global_store_dwordx4 v[56:57], v[60:63], off
	global_store_dwordx4 v[46:47], v[40:43], off
	global_store_dwordx4 v[30:31], v[24:27], off
	global_store_dwordx4 v[14:15], v[8:11], off
	global_store_dwordx4 v[12:13], v[4:7], off offset:256
	s_cbranch_vccz .LBB0_89
	s_waitcnt vmcnt(0)
	s_cmpk_gt_u32 s17, 0xff
	v_readlane_b32 s2, v254, 59
	s_cbranch_scc1 .LBB0_100
	s_barrier

; #define PG8_STAGE(bufoff, gbase, voff) do { _Pragma("unroll") for (int _i = 0; _i < 2; ++_i) \
;         __builtin_amdgcn_global_load_lds((const unsigned*)((const char*)(gbase) + (voff)[_i]), (PG8_LAS unsigned*)(lds + (bufoff) + ldsw + _i * 8192), 16, 0, 0); } while (0)
; #define PG8_LDA(dst, b, h) do { _Pragma("unroll") for (int m = 0; m < 4; ++m) _Pragma("unroll") for (int k = 0; k < 2; ++k) dst[m][k] = *(const PG8_LAS bf16x8*)(lds + PG8_SA(b, h) + aoff + m * 2048 + k * 1024); } while (0)
; #define PG8_LDB(dst, b, h) do { _Pragma("unroll") for (int n = 0; n < 2; ++n) _Pragma("unroll") for (int k = 0; k < 2; ++k) dst[n][k] = *(const PG8_LAS bf16x8*)(lds + PG8_SB(b, h) + boff + n * 2048 + k * 1024); } while (0)
; #define PG8_WAIT_V(n) asm volatile("s_waitcnt vmcnt(" #n ")" ::: "memory")
; #define PG8_WAIT_L(n) asm volatile("s_waitcnt lgkmcnt(" #n ")" ::: "memory")
; #define PG8_BAR __builtin_amdgcn_s_barrier()
; #define PG8_SCHED __builtin_amdgcn_sched_barrier(0)
; template <class Epi, class Sched>
; __device__ __forceinline__ void gemm_phase(PG8_LAS unsigned char* lds, const Gemm g, const Sched& S, const Epi& E) {
;     ...
;         const bool has_next = S.next(ui + 1, nxt);
;         const char* nA = has_next ? (const char*)g.A + (size_t)nxt.pm * tstep : cA; const char* nB = has_next ? (const char*)g.Bt + (size_t)nxt.pn * tstep : cB;
;         for (int t = 0; t < nt; t += 2) {
;             const bool last = (t == nt - 2);
;             const char* a1 = cA + (size_t)(t + 1) * kstep;
;             const char* a2 = last ? nA : cA + (size_t)(t + 2) * kstep; const char* b2 = last ? nB : cB + (size_t)(t + 2) * kstep;
;             const char* a3 = a2 + kstep; const char* b3 = b2 + kstep;
;             if (last && has_next) S.a_ready(nxt);
;             PG8_LDB(B0, 0, 0); PG8_SCHED; PG8_LDA(At, 0, 0); PG8_STAGE(PG8_SA(1, 1), a1 + hstep, voffA);
;             PG8_WAIT_L(8); PG8_BAR; PG8_WAIT_L(0); PG8_MMA(0, 0, At, B0); PG8_BAR; PG8_SCHED;
;             PG8_LDB(B1, 0, 1); PG8_STAGE(PG8_SB(0, 0), b2, voffB);
;             PG8_BAR; PG8_WAIT_L(0); PG8_MMA(0, 1, At, B1); PG8_BAR;
;             PG8_LDA(At, 0, 1); PG8_STAGE(PG8_SA(0, 0), a2, voffA);
;             PG8_BAR; PG8_WAIT_L(0); PG8_MMA(1, 0, At, B0); PG8_BAR; PG8_SCHED;
;             PG8_STAGE(PG8_SB(0, 1), b2 + hstep, voffB);
;             PG8_WAIT_V(6); PG8_BAR; PG8_MMA(1, 1, At, B1); PG8_BAR;
.LBB0_114:
	s_add_u32 s14, s12, 0xfffc0080
	s_addc_u32 s15, s13, -1
	v_add_u32_e32 v154, 0x10000, v143
	ds_read_b128 v[138:141], v154
	ds_read_b128 v[146:149], v154 offset:1024
	ds_read_b128 v[150:153], v154 offset:2048
	ds_read_b128 v[154:157], v154 offset:3072
	s_cmp_eq_u32 s45, 12
	s_cselect_b32 s17, s5, s15
	s_cselect_b32 s16, s40, s14
	s_cselect_b32 s15, s1, s44
	s_cselect_b32 s14, s41, s43
	s_add_i32 m0, s11, 0xc000
	ds_read_b128 v[158:161], v145
	ds_read_b128 v[162:165], v145 offset:1024
	ds_read_b128 v[166:169], v145 offset:2048
	ds_read_b128 v[170:173], v145 offset:3072
	ds_read_b128 v[178:181], v145 offset:4096
	ds_read_b128 v[182:185], v145 offset:5120
	ds_read_b128 v[186:189], v145 offset:6144
	ds_read_b128 v[190:193], v145 offset:7168
	global_load_lds_dwordx4 v134, s[12:13]
	s_add_i32 m0, s11, 0xe000
	s_nop 0
	global_load_lds_dwordx4 v136, s[12:13]
	s_waitcnt lgkmcnt(8)
	s_barrier
	s_waitcnt lgkmcnt(0)
	v_mfma_f32_16x16x32_bf16 v[124:127], v[138:141], v[158:161], v[124:127]
	v_mfma_f32_16x16x32_bf16 v[116:119], v[150:153], v[158:161], v[116:119]
	v_mfma_f32_16x16x32_bf16 v[108:111], v[138:141], v[166:169], v[108:111]
	v_mfma_f32_16x16x32_bf16 v[100:103], v[150:153], v[166:169], v[100:103]
	v_mfma_f32_16x16x32_bf16 v[92:95], v[138:141], v[178:181], v[92:95]
	v_mfma_f32_16x16x32_bf16 v[84:87], v[150:153], v[178:181], v[84:87]
	v_mfma_f32_16x16x32_bf16 v[76:79], v[138:141], v[186:189], v[76:79]
	v_mfma_f32_16x16x32_bf16 v[68:71], v[150:153], v[186:189], v[68:71]
	v_mfma_f32_16x16x32_bf16 v[124:127], v[146:149], v[162:165], v[124:127]
	v_mfma_f32_16x16x32_bf16 v[116:119], v[154:157], v[162:165], v[116:119]
	v_mfma_f32_16x16x32_bf16 v[108:111], v[146:149], v[170:173], v[108:111]
	v_mfma_f32_16x16x32_bf16 v[100:103], v[154:157], v[170:173], v[100:103]
	v_mfma_f32_16x16x32_bf16 v[92:95], v[146:149], v[182:185], v[92:95]
	v_mfma_f32_16x16x32_bf16 v[84:87], v[154:157], v[182:185], v[84:87]
	v_mfma_f32_16x16x32_bf16 v[76:79], v[146:149], v[190:193], v[76:79]
	v_mfma_f32_16x16x32_bf16 v[68:71], v[154:157], v[190:193], v[68:71]
	s_barrier
	s_add_i32 s48, 0, 0x14000
	v_add_u32_e32 v174, 0x14000, v143
	ds_read_b128 v[194:197], v174
	ds_read_b128 v[198:201], v174 offset:1024
	ds_read_b128 v[202:205], v174 offset:2048
	ds_read_b128 v[206:209], v174 offset:3072
	s_add_u32 s98, s14, 0x80
	s_addc_u32 s99, s15, 0
	s_add_i32 m0, s20, 0x10000
	s_nop 0
	global_load_lds_dwordx4 v176, s[14:15]
	s_add_i32 m0, s20, 0x12000
	s_nop 0
	global_load_lds_dwordx4 v128, s[14:15]
	s_barrier
	s_waitcnt lgkmcnt(0)
	v_mfma_f32_16x16x32_bf16 v[120:123], v[194:197], v[158:161], v[120:123]
	v_mfma_f32_16x16x32_bf16 v[112:115], v[202:205], v[158:161], v[112:115]
	v_mfma_f32_16x16x32_bf16 v[104:107], v[194:197], v[166:169], v[104:107]
	v_mfma_f32_16x16x32_bf16 v[96:99], v[202:205], v[166:169], v[96:99]
	v_mfma_f32_16x16x32_bf16 v[88:91], v[194:197], v[178:181], v[88:91]
	v_mfma_f32_16x16x32_bf16 v[80:83], v[202:205], v[178:181], v[80:83]
	v_mfma_f32_16x16x32_bf16 v[72:75], v[194:197], v[186:189], v[72:75]
	v_mfma_f32_16x16x32_bf16 v[64:67], v[202:205], v[186:189], v[64:67]
	v_mfma_f32_16x16x32_bf16 v[120:123], v[198:201], v[162:165], v[120:123]
	v_mfma_f32_16x16x32_bf16 v[112:115], v[206:209], v[162:165], v[112:115]
	v_mfma_f32_16x16x32_bf16 v[104:107], v[198:201], v[170:173], v[104:107]
	v_mfma_f32_16x16x32_bf16 v[96:99], v[206:209], v[170:173], v[96:99]
	v_mfma_f32_16x16x32_bf16 v[88:91], v[198:201], v[182:185], v[88:91]
	v_mfma_f32_16x16x32_bf16 v[80:83], v[206:209], v[182:185], v[80:83]
	v_mfma_f32_16x16x32_bf16 v[72:75], v[198:201], v[190:193], v[72:75]
	v_mfma_f32_16x16x32_bf16 v[64:67], v[206:209], v[190:193], v[64:67]
	s_mov_b32 m0, s11
	s_add_u32 s100, s16, 0x80
	s_addc_u32 s101, s17, 0
	s_barrier
	ds_read_b128 v[158:161], v145 offset:16384
	ds_read_b128 v[162:165], v145 offset:17408
	ds_read_b128 v[166:169], v145 offset:18432
	ds_read_b128 v[170:173], v145 offset:19456
	ds_read_b128 v[178:181], v145 offset:20480
	ds_read_b128 v[182:185], v145 offset:21504
	ds_read_b128 v[186:189], v145 offset:22528
	ds_read_b128 v[190:193], v145 offset:23552
	global_load_lds_dwordx4 v132, s[16:17]
	s_mov_b32 m0, s22
	s_nop 0
	global_load_lds_dwordx4 v130, s[16:17]
	s_barrier
	s_waitcnt lgkmcnt(0)
	v_mfma_f32_16x16x32_bf16 v[60:63], v[138:141], v[158:161], v[60:63]
	v_mfma_f32_16x16x32_bf16 v[52:55], v[150:153], v[158:161], v[52:55]
	v_mfma_f32_16x16x32_bf16 v[44:47], v[138:141], v[166:169], v[44:47]
	v_mfma_f32_16x16x32_bf16 v[36:39], v[150:153], v[166:169], v[36:39]
	v_mfma_f32_16x16x32_bf16 v[28:31], v[138:141], v[178:181], v[28:31]
	v_mfma_f32_16x16x32_bf16 v[20:23], v[150:153], v[178:181], v[20:23]
	v_mfma_f32_16x16x32_bf16 v[12:15], v[138:141], v[186:189], v[12:15]
	v_mfma_f32_16x16x32_bf16 v[4:7], v[150:153], v[186:189], v[4:7]
	v_mfma_f32_16x16x32_bf16 v[60:63], v[146:149], v[162:165], v[60:63]
	v_mfma_f32_16x16x32_bf16 v[52:55], v[154:157], v[162:165], v[52:55]
	v_mfma_f32_16x16x32_bf16 v[44:47], v[146:149], v[170:173], v[44:47]
	v_mfma_f32_16x16x32_bf16 v[36:39], v[154:157], v[170:173], v[36:39]
	v_mfma_f32_16x16x32_bf16 v[28:31], v[146:149], v[182:185], v[28:31]
	v_mfma_f32_16x16x32_bf16 v[20:23], v[154:157], v[182:185], v[20:23]
	v_mfma_f32_16x16x32_bf16 v[12:15], v[146:149], v[190:193], v[12:15]
	v_mfma_f32_16x16x32_bf16 v[4:7], v[154:157], v[190:193], v[4:7]
	s_barrier
	s_add_u32 s46, s14, 0x40000
	s_addc_u32 s47, s15, 0
	s_add_i32 m0, s20, 0x14000
	s_nop 0
	global_load_lds_dwordx4 v176, s[46:47]
	s_add_i32 m0, s20, 0x16000
	s_nop 0
	global_load_lds_dwordx4 v128, s[46:47]
	s_waitcnt vmcnt(6)
	s_barrier
; #define PG8_STAGE(bufoff, gbase, voff) do { _Pragma("unroll") for (int _i = 0; _i < 2; ++_i) \
;         __builtin_amdgcn_global_load_lds((const unsigned*)((const char*)(gbase) + (voff)[_i]), (PG8_LAS unsigned*)(lds + (bufoff) + ldsw + _i * 8192), 16, 0, 0); } while (0)
; #define PG8_LDA(dst, b, h) do { _Pragma("unroll") for (int m = 0; m < 4; ++m) _Pragma("unroll") for (int k = 0; k < 2; ++k) dst[m][k] = *(const PG8_LAS bf16x8*)(lds + PG8_SA(b, h) + aoff + m * 2048 + k * 1024); } while (0)
; #define PG8_LDB(dst, b, h) do { _Pragma("unroll") for (int n = 0; n < 2; ++n) _Pragma("unroll") for (int k = 0; k < 2; ++k) dst[n][k] = *(const PG8_LAS bf16x8*)(lds + PG8_SB(b, h) + boff + n * 2048 + k * 1024); } while (0)
; #define PG8_MMA(ai, bj, At, Bt) do { __builtin_amdgcn_s_setprio(1); _Pragma("unroll") for (int m = 0; m < 4; ++m) _Pragma("unroll") for (int n = 0; n < 2; ++n) _Pragma("unroll") for (int k = 0; k < 2; ++k) \
;         acc[ai][bj][m][n] = __builtin_amdgcn_mfma_f32_16x16x32_bf16(Bt[n][k], At[m][k], acc[ai][bj][m][n], 0, 0, 0); __builtin_amdgcn_s_setprio(0); } while (0)
; #define PG8_WAIT_V(n) asm volatile("s_waitcnt vmcnt(" #n ")" ::: "memory")
; #define PG8_WAIT_L(n) asm volatile("s_waitcnt lgkmcnt(" #n ")" ::: "memory")
; #define PG8_BAR __builtin_amdgcn_s_barrier()
; #define PG8_SCHED __builtin_amdgcn_sched_barrier(0)
; template <class Epi, class Sched>
; __device__ __forceinline__ void gemm_phase(PG8_LAS unsigned char* lds, const Gemm g, const Sched& S, const Epi& E) {
;     ...
;             PG8_WAIT_V(6); PG8_BAR; PG8_MMA(1, 1, At, B1); PG8_BAR;
;             PG8_LDB(B0, 1, 0); PG8_SCHED; PG8_LDA(At, 1, 0); PG8_STAGE(PG8_SA(0, 1), a2 + hstep, voffA);
;             PG8_WAIT_L(8); PG8_BAR; PG8_WAIT_L(0); PG8_MMA(0, 0, At, B0); PG8_BAR; PG8_SCHED;
;             PG8_LDB(B1, 1, 1); PG8_STAGE(PG8_SB(1, 0), b3, voffB);
;             PG8_BAR; PG8_WAIT_L(0); PG8_MMA(0, 1, At, B1); PG8_BAR;
;             PG8_LDA(At, 1, 1); PG8_STAGE(PG8_SA(1, 0), a3, voffA);
	v_mfma_f32_16x16x32_bf16 v[56:59], v[194:197], v[158:161], v[56:59]
	v_mfma_f32_16x16x32_bf16 v[48:51], v[202:205], v[158:161], v[48:51]
	v_mfma_f32_16x16x32_bf16 v[40:43], v[194:197], v[166:169], v[40:43]
	v_mfma_f32_16x16x32_bf16 v[32:35], v[202:205], v[166:169], v[32:35]
	v_mfma_f32_16x16x32_bf16 v[24:27], v[194:197], v[178:181], v[24:27]
	v_mfma_f32_16x16x32_bf16 v[16:19], v[202:205], v[178:181], v[16:19]
	v_mfma_f32_16x16x32_bf16 v[8:11], v[194:197], v[186:189], v[8:11]
	v_mfma_f32_16x16x32_bf16 v[0:3], v[202:205], v[186:189], v[0:3]
	v_mfma_f32_16x16x32_bf16 v[56:59], v[198:201], v[162:165], v[56:59]
	v_mfma_f32_16x16x32_bf16 v[48:51], v[206:209], v[162:165], v[48:51]
	v_mfma_f32_16x16x32_bf16 v[40:43], v[198:201], v[170:173], v[40:43]
	v_mfma_f32_16x16x32_bf16 v[32:35], v[206:209], v[170:173], v[32:35]
	v_mfma_f32_16x16x32_bf16 v[24:27], v[198:201], v[182:185], v[24:27]
	v_mfma_f32_16x16x32_bf16 v[16:19], v[206:209], v[182:185], v[16:19]
	v_mfma_f32_16x16x32_bf16 v[8:11], v[198:201], v[190:193], v[8:11]
	v_mfma_f32_16x16x32_bf16 v[0:3], v[206:209], v[190:193], v[0:3]
	v_add_u32_e32 v154, 0x18000, v143
	s_barrier
	ds_read_b128 v[138:141], v154
	ds_read_b128 v[146:149], v154 offset:1024
	ds_read_b128 v[150:153], v154 offset:2048
	ds_read_b128 v[154:157], v154 offset:3072
	s_add_u32 s16, s16, 0x40000
	s_addc_u32 s17, s17, 0
	s_mov_b32 m0, s23
	ds_read_b128 v[158:161], v145 offset:32768
	ds_read_b128 v[162:165], v145 offset:33792
	ds_read_b128 v[166:169], v145 offset:34816
	ds_read_b128 v[170:173], v145 offset:35840
	ds_read_b128 v[178:181], v145 offset:36864
	ds_read_b128 v[182:185], v145 offset:37888
	ds_read_b128 v[186:189], v145 offset:38912
	ds_read_b128 v[190:193], v145 offset:39936
	global_load_lds_dwordx4 v132, s[16:17]
	s_mov_b32 m0, s26
	s_nop 0
	global_load_lds_dwordx4 v130, s[16:17]
	s_waitcnt lgkmcnt(8)
	s_barrier
	s_waitcnt lgkmcnt(0)
	v_mfma_f32_16x16x32_bf16 v[124:127], v[138:141], v[158:161], v[124:127]
	v_mfma_f32_16x16x32_bf16 v[116:119], v[150:153], v[158:161], v[116:119]
	v_mfma_f32_16x16x32_bf16 v[108:111], v[138:141], v[166:169], v[108:111]
	v_mfma_f32_16x16x32_bf16 v[100:103], v[150:153], v[166:169], v[100:103]
	v_mfma_f32_16x16x32_bf16 v[92:95], v[138:141], v[178:181], v[92:95]
	v_mfma_f32_16x16x32_bf16 v[84:87], v[150:153], v[178:181], v[84:87]
	v_mfma_f32_16x16x32_bf16 v[76:79], v[138:141], v[186:189], v[76:79]
	v_mfma_f32_16x16x32_bf16 v[68:71], v[150:153], v[186:189], v[68:71]
	v_mfma_f32_16x16x32_bf16 v[124:127], v[146:149], v[162:165], v[124:127]
	v_mfma_f32_16x16x32_bf16 v[116:119], v[154:157], v[162:165], v[116:119]
	v_mfma_f32_16x16x32_bf16 v[108:111], v[146:149], v[170:173], v[108:111]
	v_mfma_f32_16x16x32_bf16 v[100:103], v[154:157], v[170:173], v[100:103]
	v_mfma_f32_16x16x32_bf16 v[92:95], v[146:149], v[182:185], v[92:95]
	v_mfma_f32_16x16x32_bf16 v[84:87], v[154:157], v[182:185], v[84:87]
	v_mfma_f32_16x16x32_bf16 v[76:79], v[146:149], v[190:193], v[76:79]
	v_mfma_f32_16x16x32_bf16 v[68:71], v[154:157], v[190:193], v[68:71]
	s_barrier
	v_add_u32_e32 v206, 0x1c000, v143
	s_add_i32 m0, s20, 0x18000
	ds_read_b128 v[194:197], v206
	ds_read_b128 v[198:201], v206 offset:1024
	ds_read_b128 v[202:205], v206 offset:2048
	ds_read_b128 v[206:209], v206 offset:3072
	global_load_lds_dwordx4 v176, s[98:99]
	s_add_i32 m0, s20, 0x1a000
	s_nop 0
	global_load_lds_dwordx4 v128, s[98:99]
	s_barrier
	s_waitcnt lgkmcnt(0)
	v_mfma_f32_16x16x32_bf16 v[120:123], v[194:197], v[158:161], v[120:123]
	v_mfma_f32_16x16x32_bf16 v[112:115], v[202:205], v[158:161], v[112:115]
	v_mfma_f32_16x16x32_bf16 v[104:107], v[194:197], v[166:169], v[104:107]
	v_mfma_f32_16x16x32_bf16 v[96:99], v[202:205], v[166:169], v[96:99]
	v_mfma_f32_16x16x32_bf16 v[88:91], v[194:197], v[178:181], v[88:91]
	v_mfma_f32_16x16x32_bf16 v[80:83], v[202:205], v[178:181], v[80:83]
	v_mfma_f32_16x16x32_bf16 v[72:75], v[194:197], v[186:189], v[72:75]
	v_mfma_f32_16x16x32_bf16 v[64:67], v[202:205], v[186:189], v[64:67]
	v_mfma_f32_16x16x32_bf16 v[120:123], v[198:201], v[162:165], v[120:123]
	v_mfma_f32_16x16x32_bf16 v[112:115], v[206:209], v[162:165], v[112:115]
	v_mfma_f32_16x16x32_bf16 v[104:107], v[198:201], v[170:173], v[104:107]
	v_mfma_f32_16x16x32_bf16 v[96:99], v[206:209], v[170:173], v[96:99]
	v_mfma_f32_16x16x32_bf16 v[88:91], v[198:201], v[182:185], v[88:91]
	v_mfma_f32_16x16x32_bf16 v[80:83], v[206:209], v[182:185], v[80:83]
	v_mfma_f32_16x16x32_bf16 v[72:75], v[198:201], v[190:193], v[72:75]
	v_mfma_f32_16x16x32_bf16 v[64:67], v[206:209], v[190:193], v[64:67]
	s_mov_b32 m0, s28
	s_barrier
	ds_read_b128 v[158:161], v145 offset:49152
	ds_read_b128 v[162:165], v145 offset:50176
	ds_read_b128 v[166:169], v145 offset:51200
	ds_read_b128 v[170:173], v145 offset:52224
	ds_read_b128 v[178:181], v145 offset:53248
	ds_read_b128 v[182:185], v145 offset:54272
	ds_read_b128 v[186:189], v145 offset:55296
	ds_read_b128 v[190:193], v145 offset:56320
	global_load_lds_dwordx4 v132, s[100:101]
	s_mov_b32 m0, s29
	s_nop 0
	global_load_lds_dwordx4 v130, s[100:101]
	s_barrier
	s_waitcnt lgkmcnt(0)
	v_mfma_f32_16x16x32_bf16 v[60:63], v[138:141], v[158:161], v[60:63]
	v_mfma_f32_16x16x32_bf16 v[52:55], v[150:153], v[158:161], v[52:55]
	v_mfma_f32_16x16x32_bf16 v[44:47], v[138:141], v[166:169], v[44:47]
	v_mfma_f32_16x16x32_bf16 v[36:39], v[150:153], v[166:169], v[36:39]
	v_mfma_f32_16x16x32_bf16 v[28:31], v[138:141], v[178:181], v[28:31]
	v_mfma_f32_16x16x32_bf16 v[20:23], v[150:153], v[178:181], v[20:23]
	v_mfma_f32_16x16x32_bf16 v[12:15], v[138:141], v[186:189], v[12:15]
	v_mfma_f32_16x16x32_bf16 v[4:7], v[150:153], v[186:189], v[4:7]
	v_mfma_f32_16x16x32_bf16 v[60:63], v[146:149], v[162:165], v[60:63]
	v_mfma_f32_16x16x32_bf16 v[52:55], v[154:157], v[162:165], v[52:55]
	v_mfma_f32_16x16x32_bf16 v[44:47], v[146:149], v[170:173], v[44:47]
	v_mfma_f32_16x16x32_bf16 v[36:39], v[154:157], v[170:173], v[36:39]
	v_mfma_f32_16x16x32_bf16 v[28:31], v[146:149], v[182:185], v[28:31]
	v_mfma_f32_16x16x32_bf16 v[20:23], v[154:157], v[182:185], v[20:23]
	v_mfma_f32_16x16x32_bf16 v[12:15], v[146:149], v[190:193], v[12:15]
	v_mfma_f32_16x16x32_bf16 v[4:7], v[154:157], v[190:193], v[4:7]
	s_barrier
; __device__ __forceinline__ unsigned cvtpk(float lo, float hi) { const f32x2 v = (f32x2){lo, hi}; const bf16v2 b = __builtin_convertvector(v, bf16v2); return __builtin_bit_cast(unsigned, b); }
; __device__ __forceinline__ float siluf_(float x) { return x * sigmoidf_(x); }
; #define PG8_STAGE(bufoff, gbase, voff) do { _Pragma("unroll") for (int _i = 0; _i < 2; ++_i) \
;         __builtin_amdgcn_global_load_lds((const unsigned*)((const char*)(gbase) + (voff)[_i]), (PG8_LAS unsigned*)(lds + (bufoff) + ldsw + _i * 8192), 16, 0, 0); } while (0)
; #define PG8_LDA(dst, b, h) do { _Pragma("unroll") for (int m = 0; m < 4; ++m) _Pragma("unroll") for (int k = 0; k < 2; ++k) dst[m][k] = *(const PG8_LAS bf16x8*)(lds + PG8_SA(b, h) + aoff + m * 2048 + k * 1024); } while (0)
; #define PG8_WAIT_V(n) asm volatile("s_waitcnt vmcnt(" #n ")" ::: "memory")
; #define PG8_WAIT_L(n) asm volatile("s_waitcnt lgkmcnt(" #n ")" ::: "memory")
; #define PG8_BAR __builtin_amdgcn_s_barrier()
; #define PG8_SCHED __builtin_amdgcn_sched_barrier(0)
; template <class Epi, class Sched>
; __device__ __forceinline__ void gemm_phase(PG8_LAS unsigned char* lds, const Gemm g, const Sched& S, const Epi& E) {
;     ...
;             PG8_LDA(At, 1, 1); PG8_STAGE(PG8_SA(1, 0), a3, voffA);
;             PG8_BAR; PG8_WAIT_L(0); PG8_MMA(1, 0, At, B0); PG8_BAR; PG8_SCHED;
;             PG8_STAGE(PG8_SB(1, 1), b3 + hstep, voffB);
;             PG8_WAIT_V(6); PG8_BAR; PG8_MMA(1, 1, At, B1); PG8_BAR;
;         }
;     __device__ __forceinline__ void operator()(const f32x4 (&acc)[2][2][4][2], const pg8::Unit& u, int wr, int wc, int fr, int fq) const {
;         const int row0 = u.pm * 256 + wr * 64 + fr, col0 = u.pn * 128 + wc * 32 + 8 * fq;
; #pragma unroll
;         for (int ai = 0; ai < 2; ++ai)
; #pragma unroll
;             for (int m = 0; m < 4; ++m) { bf16_t* rowp = O + (size_t)(row0 + ai * 128 + m * 16) * ldc + col0;
;                 const f32x4 g0 = acc[ai][0][m][0], g1 = acc[ai][0][m][1], u0 = acc[ai][1][m][0], u1 = acc[ai][1][m][1];
;                 u32x4 w; w.x = cvtpk(siluf_(g0[0]) * u0[0], siluf_(g0[1]) * u0[1]); w.y = cvtpk(siluf_(g0[2]) * u0[2], siluf_(g0[3]) * u0[3]);
;                 w.z = cvtpk(siluf_(g1[0]) * u1[0], siluf_(g1[1]) * u1[1]); w.w = cvtpk(siluf_(g1[2]) * u1[2], siluf_(g1[3]) * u1[3]);
;                 *(u32x4*)rowp = w; }
	s_add_u32 s14, s14, 0x40080
	s_addc_u32 s15, s15, 0
	s_add_i32 m0, s20, 0x1c000
	s_nop 0
	global_load_lds_dwordx4 v176, s[14:15]
	s_add_i32 m0, s20, 0x1e000
	s_nop 0
	global_load_lds_dwordx4 v128, s[14:15]
	s_waitcnt vmcnt(6)
	s_barrier
	v_mfma_f32_16x16x32_bf16 v[56:59], v[194:197], v[158:161], v[56:59]
	v_mfma_f32_16x16x32_bf16 v[48:51], v[202:205], v[158:161], v[48:51]
	v_mfma_f32_16x16x32_bf16 v[40:43], v[194:197], v[166:169], v[40:43]
	v_mfma_f32_16x16x32_bf16 v[32:35], v[202:205], v[166:169], v[32:35]
	v_mfma_f32_16x16x32_bf16 v[24:27], v[194:197], v[178:181], v[24:27]
	v_mfma_f32_16x16x32_bf16 v[16:19], v[202:205], v[178:181], v[16:19]
	v_mfma_f32_16x16x32_bf16 v[8:11], v[194:197], v[186:189], v[8:11]
	v_mfma_f32_16x16x32_bf16 v[0:3], v[202:205], v[186:189], v[0:3]
	v_mfma_f32_16x16x32_bf16 v[56:59], v[198:201], v[162:165], v[56:59]
	v_mfma_f32_16x16x32_bf16 v[48:51], v[206:209], v[162:165], v[48:51]
	v_mfma_f32_16x16x32_bf16 v[40:43], v[198:201], v[170:173], v[40:43]
	v_mfma_f32_16x16x32_bf16 v[32:35], v[206:209], v[170:173], v[32:35]
	v_mfma_f32_16x16x32_bf16 v[24:27], v[198:201], v[182:185], v[24:27]
	v_mfma_f32_16x16x32_bf16 v[16:19], v[206:209], v[182:185], v[16:19]
	v_mfma_f32_16x16x32_bf16 v[8:11], v[198:201], v[190:193], v[8:11]
	v_mfma_f32_16x16x32_bf16 v[0:3], v[206:209], v[190:193], v[0:3]
	s_add_i32 s45, s45, 2
	s_add_u32 s12, s12, 0x100
	s_addc_u32 s13, s13, 0
	s_add_u32 s43, s43, 0x100
	s_addc_u32 s44, s44, 0
	s_cmp_gt_u32 s45, 13
	s_barrier
	s_cbranch_scc0 .LBB0_114
	v_mul_f32_e32 v147, 0xbfb8aa3b, v124
	v_exp_f32_e32 v147, v147
	v_readlane_b32 s12, v253, 16
	v_lshl_add_u32 v146, s10, 8, v142
	v_lshl_or_b32 v140, s34, 7, v144
	v_add_f32_e32 v147, 1.0, v147
	v_rcp_f32_e32 v150, v147
	v_mul_f32_e32 v147, 0xbfb8aa3b, v125
	v_exp_f32_e32 v147, v147
	v_readlane_b32 s13, v253, 17
	v_ashrrev_i32_e32 v141, 31, v140
	v_lshlrev_b64 v[140:141], 1, v[140:141]
	v_add_f32_e32 v147, 1.0, v147
	v_rcp_f32_e32 v151, v147
	v_mov_b64_e32 v[138:139], s[12:13]
	v_mad_i64_i32 v[148:149], s[12:13], v146, s81, v[138:139]
	v_pk_mul_f32 v[124:125], v[124:125], v[150:151]
	v_lshl_add_u64 v[148:149], v[148:149], 0, v[140:141]
	v_pk_mul_f32 v[120:121], v[124:125], v[120:121]
	s_and_b64 vcc, exec, s[38:39]
	v_cvt_pk_bf16_f32 v120, v120, v121
	v_mul_f32_e32 v121, 0xbfb8aa3b, v126
	v_exp_f32_e32 v121, v121
	s_mov_b32 s34, s0
	s_mov_b32 s10, s4
	s_mov_b64 s[14:15], s[8:9]
	v_add_f32_e32 v121, 1.0, v121
	v_rcp_f32_e32 v124, v121
	v_mul_f32_e32 v121, 0xbfb8aa3b, v127
	v_exp_f32_e32 v121, v121
	s_nop 0
	v_add_f32_e32 v121, 1.0, v121
	v_rcp_f32_e32 v125, v121
	s_nop 0
	v_pk_mul_f32 v[124:125], v[126:127], v[124:125]
	s_nop 0
	v_pk_mul_f32 v[122:123], v[124:125], v[122:123]
	s_nop 0
	v_cvt_pk_bf16_f32 v121, v122, v123
	v_mul_f32_e32 v122, 0xbfb8aa3b, v116
	v_mul_f32_e32 v123, 0xbfb8aa3b, v117
	v_exp_f32_e32 v122, v122
	v_exp_f32_e32 v123, v123
	v_add_f32_e32 v122, 1.0, v122
	v_add_f32_e32 v123, 1.0, v123
	v_rcp_f32_e32 v122, v122
	v_rcp_f32_e32 v123, v123
	s_nop 0
	v_pk_mul_f32 v[116:117], v[116:117], v[122:123]
	s_nop 0
	v_pk_mul_f32 v[112:113], v[116:117], v[112:113]
	s_nop 0
	v_cvt_pk_bf16_f32 v122, v112, v113
	v_mul_f32_e32 v112, 0xbfb8aa3b, v118
	v_mul_f32_e32 v113, 0xbfb8aa3b, v119
	v_exp_f32_e32 v112, v112
	v_exp_f32_e32 v113, v113
	v_add_f32_e32 v112, 1.0, v112
	v_add_f32_e32 v113, 1.0, v113
	v_rcp_f32_e32 v112, v112
	v_rcp_f32_e32 v113, v113
	s_nop 0
	v_pk_mul_f32 v[112:113], v[118:119], v[112:113]
	s_nop 0
	v_pk_mul_f32 v[112:113], v[112:113], v[114:115]
	v_mul_f32_e32 v114, 0xbfb8aa3b, v108
	v_mul_f32_e32 v115, 0xbfb8aa3b, v109
	v_exp_f32_e32 v114, v114
	v_exp_f32_e32 v115, v115
	v_cvt_pk_bf16_f32 v123, v112, v113
	v_or_b32_e32 v112, 16, v146
	v_add_f32_e32 v114, 1.0, v114
	v_add_f32_e32 v115, 1.0, v115
	v_rcp_f32_e32 v114, v114
	v_rcp_f32_e32 v115, v115
	v_mad_i64_i32 v[112:113], s[12:13], v112, s81, v[138:139]
	v_lshl_add_u64 v[112:113], v[112:113], 0, v[140:141]
	v_pk_mul_f32 v[108:109], v[108:109], v[114:115]
	global_store_dwordx4 v[148:149], v[120:123], off
	v_pk_mul_f32 v[104:105], v[108:109], v[104:105]
	s_nop 0
	v_cvt_pk_bf16_f32 v104, v104, v105
	v_mul_f32_e32 v105, 0xbfb8aa3b, v110
	v_exp_f32_e32 v105, v105
	s_nop 0
	v_add_f32_e32 v105, 1.0, v105
	v_rcp_f32_e32 v108, v105
	v_mul_f32_e32 v105, 0xbfb8aa3b, v111
	v_exp_f32_e32 v105, v105
	s_nop 0
	v_add_f32_e32 v105, 1.0, v105
	v_rcp_f32_e32 v109, v105
	s_nop 0
	v_pk_mul_f32 v[108:109], v[110:111], v[108:109]
	s_nop 0
	v_pk_mul_f32 v[106:107], v[108:109], v[106:107]
	s_nop 0
	v_cvt_pk_bf16_f32 v105, v106, v107
	v_mul_f32_e32 v106, 0xbfb8aa3b, v100
	v_mul_f32_e32 v107, 0xbfb8aa3b, v101
	v_exp_f32_e32 v106, v106
	v_exp_f32_e32 v107, v107
	v_add_f32_e32 v106, 1.0, v106
	v_add_f32_e32 v107, 1.0, v107
	v_rcp_f32_e32 v106, v106
	v_rcp_f32_e32 v107, v107
	s_nop 0
	v_pk_mul_f32 v[100:101], v[100:101], v[106:107]
	s_nop 0
	v_pk_mul_f32 v[96:97], v[100:101], v[96:97]
	s_nop 0
	v_cvt_pk_bf16_f32 v106, v96, v97
	v_mul_f32_e32 v96, 0xbfb8aa3b, v102
	v_mul_f32_e32 v97, 0xbfb8aa3b, v103
	v_exp_f32_e32 v96, v96
	v_exp_f32_e32 v97, v97
	v_add_f32_e32 v96, 1.0, v96
	v_add_f32_e32 v97, 1.0, v97
	v_rcp_f32_e32 v96, v96
	v_rcp_f32_e32 v97, v97
	s_nop 0
	v_pk_mul_f32 v[96:97], v[102:103], v[96:97]
	s_nop 0
	v_pk_mul_f32 v[96:97], v[96:97], v[98:99]
	v_mul_f32_e32 v98, 0xbfb8aa3b, v92
	v_mul_f32_e32 v99, 0xbfb8aa3b, v93
	v_exp_f32_e32 v98, v98
	v_exp_f32_e32 v99, v99
	v_cvt_pk_bf16_f32 v107, v96, v97
	v_or_b32_e32 v96, 32, v146
	v_add_f32_e32 v98, 1.0, v98
	v_add_f32_e32 v99, 1.0, v99
	v_rcp_f32_e32 v98, v98
	v_rcp_f32_e32 v99, v99
	v_mad_i64_i32 v[96:97], s[12:13], v96, s81, v[138:139]
; __device__ __forceinline__ unsigned cvtpk(float lo, float hi) { const f32x2 v = (f32x2){lo, hi}; const bf16v2 b = __builtin_convertvector(v, bf16v2); return __builtin_bit_cast(unsigned, b); }
; __device__ __forceinline__ float siluf_(float x) { return x * sigmoidf_(x); }
;     __device__ __forceinline__ void operator()(const f32x4 (&acc)[2][2][4][2], const pg8::Unit& u, int wr, int wc, int fr, int fq) const {
;         const int row0 = u.pm * 256 + wr * 64 + fr, col0 = u.pn * 128 + wc * 32 + 8 * fq;
; #pragma unroll
;         for (int ai = 0; ai < 2; ++ai)
; #pragma unroll
;             for (int m = 0; m < 4; ++m) { bf16_t* rowp = O + (size_t)(row0 + ai * 128 + m * 16) * ldc + col0;
;                 const f32x4 g0 = acc[ai][0][m][0], g1 = acc[ai][0][m][1], u0 = acc[ai][1][m][0], u1 = acc[ai][1][m][1];
;                 u32x4 w; w.x = cvtpk(siluf_(g0[0]) * u0[0], siluf_(g0[1]) * u0[1]); w.y = cvtpk(siluf_(g0[2]) * u0[2], siluf_(g0[3]) * u0[3]);
;                 w.z = cvtpk(siluf_(g1[0]) * u1[0], siluf_(g1[1]) * u1[1]); w.w = cvtpk(siluf_(g1[2]) * u1[2], siluf_(g1[3]) * u1[3]);
;                 *(u32x4*)rowp = w; }
	v_lshl_add_u64 v[96:97], v[96:97], 0, v[140:141]
	v_pk_mul_f32 v[92:93], v[92:93], v[98:99]
	global_store_dwordx4 v[112:113], v[104:107], off
	v_pk_mul_f32 v[88:89], v[92:93], v[88:89]
	s_nop 0
	v_cvt_pk_bf16_f32 v88, v88, v89
	v_mul_f32_e32 v89, 0xbfb8aa3b, v94
	v_exp_f32_e32 v89, v89
	s_nop 0
	v_add_f32_e32 v89, 1.0, v89
	v_rcp_f32_e32 v92, v89
	v_mul_f32_e32 v89, 0xbfb8aa3b, v95
	v_exp_f32_e32 v89, v89
	s_nop 0
	v_add_f32_e32 v89, 1.0, v89
	v_rcp_f32_e32 v93, v89
	s_nop 0
	v_pk_mul_f32 v[92:93], v[94:95], v[92:93]
	s_nop 0
	v_pk_mul_f32 v[90:91], v[92:93], v[90:91]
	s_nop 0
	v_cvt_pk_bf16_f32 v89, v90, v91
	v_mul_f32_e32 v90, 0xbfb8aa3b, v84
	v_mul_f32_e32 v91, 0xbfb8aa3b, v85
	v_exp_f32_e32 v90, v90
	v_exp_f32_e32 v91, v91
	v_add_f32_e32 v90, 1.0, v90
	v_add_f32_e32 v91, 1.0, v91
	v_rcp_f32_e32 v90, v90
	v_rcp_f32_e32 v91, v91
	s_nop 0
	v_pk_mul_f32 v[84:85], v[84:85], v[90:91]
	s_nop 0
	v_pk_mul_f32 v[80:81], v[84:85], v[80:81]
	s_nop 0
	v_cvt_pk_bf16_f32 v90, v80, v81
	v_mul_f32_e32 v80, 0xbfb8aa3b, v86
	v_mul_f32_e32 v81, 0xbfb8aa3b, v87
	v_exp_f32_e32 v80, v80
	v_exp_f32_e32 v81, v81
	v_add_f32_e32 v80, 1.0, v80
	v_add_f32_e32 v81, 1.0, v81
	v_rcp_f32_e32 v80, v80
	v_rcp_f32_e32 v81, v81
	s_nop 0
	v_pk_mul_f32 v[80:81], v[86:87], v[80:81]
	s_nop 0
	v_pk_mul_f32 v[80:81], v[80:81], v[82:83]
	v_mul_f32_e32 v82, 0xbfb8aa3b, v76
	v_mul_f32_e32 v83, 0xbfb8aa3b, v77
	v_exp_f32_e32 v82, v82
	v_exp_f32_e32 v83, v83
	v_cvt_pk_bf16_f32 v91, v80, v81
	v_or_b32_e32 v80, 48, v146
	v_add_f32_e32 v82, 1.0, v82
	v_add_f32_e32 v83, 1.0, v83
	v_rcp_f32_e32 v82, v82
	v_rcp_f32_e32 v83, v83
	v_mad_i64_i32 v[80:81], s[12:13], v80, s81, v[138:139]
	v_lshl_add_u64 v[80:81], v[80:81], 0, v[140:141]
	v_pk_mul_f32 v[76:77], v[76:77], v[82:83]
	global_store_dwordx4 v[96:97], v[88:91], off
	v_pk_mul_f32 v[72:73], v[76:77], v[72:73]
	s_nop 0
	v_cvt_pk_bf16_f32 v72, v72, v73
	v_mul_f32_e32 v73, 0xbfb8aa3b, v78
	v_exp_f32_e32 v73, v73
	s_nop 0
	v_add_f32_e32 v73, 1.0, v73
	v_rcp_f32_e32 v76, v73
	v_mul_f32_e32 v73, 0xbfb8aa3b, v79
	v_exp_f32_e32 v73, v73
	s_nop 0
	v_add_f32_e32 v73, 1.0, v73
	v_rcp_f32_e32 v77, v73
	s_nop 0
	v_pk_mul_f32 v[76:77], v[78:79], v[76:77]
	s_nop 0
	v_pk_mul_f32 v[74:75], v[76:77], v[74:75]
	s_nop 0
	v_cvt_pk_bf16_f32 v73, v74, v75
	v_mul_f32_e32 v74, 0xbfb8aa3b, v68
	v_mul_f32_e32 v75, 0xbfb8aa3b, v69
	v_exp_f32_e32 v74, v74
	v_exp_f32_e32 v75, v75
	v_add_f32_e32 v74, 1.0, v74
	v_add_f32_e32 v75, 1.0, v75
	v_rcp_f32_e32 v74, v74
	v_rcp_f32_e32 v75, v75
	s_nop 0
	v_pk_mul_f32 v[68:69], v[68:69], v[74:75]
	s_nop 0
	v_pk_mul_f32 v[64:65], v[68:69], v[64:65]
	s_nop 0
	v_cvt_pk_bf16_f32 v74, v64, v65
	v_mul_f32_e32 v64, 0xbfb8aa3b, v70
	v_mul_f32_e32 v65, 0xbfb8aa3b, v71
	v_exp_f32_e32 v64, v64
	v_exp_f32_e32 v65, v65
	v_add_f32_e32 v64, 1.0, v64
	v_add_f32_e32 v65, 1.0, v65
	v_rcp_f32_e32 v64, v64
	v_rcp_f32_e32 v65, v65
	s_nop 0
	v_pk_mul_f32 v[64:65], v[70:71], v[64:65]
	s_nop 0
	v_pk_mul_f32 v[64:65], v[64:65], v[66:67]
	v_mul_f32_e32 v66, 0xbfb8aa3b, v60
	v_mul_f32_e32 v67, 0xbfb8aa3b, v61
	v_exp_f32_e32 v66, v66
	v_exp_f32_e32 v67, v67
	v_cvt_pk_bf16_f32 v75, v64, v65
	v_add_u32_e32 v64, 0x80, v146
	v_add_f32_e32 v66, 1.0, v66
	v_add_f32_e32 v67, 1.0, v67
	v_rcp_f32_e32 v66, v66
	v_rcp_f32_e32 v67, v67
	v_mad_i64_i32 v[64:65], s[12:13], v64, s81, v[138:139]
	v_lshl_add_u64 v[64:65], v[64:65], 0, v[140:141]
	v_pk_mul_f32 v[60:61], v[60:61], v[66:67]
	global_store_dwordx4 v[80:81], v[72:75], off
	v_pk_mul_f32 v[56:57], v[60:61], v[56:57]
	s_nop 0
	v_cvt_pk_bf16_f32 v56, v56, v57
	v_mul_f32_e32 v57, 0xbfb8aa3b, v62
	v_exp_f32_e32 v57, v57
	s_nop 0
	v_add_f32_e32 v57, 1.0, v57
	v_rcp_f32_e32 v60, v57
	v_mul_f32_e32 v57, 0xbfb8aa3b, v63
	v_exp_f32_e32 v57, v57
	s_nop 0
	v_add_f32_e32 v57, 1.0, v57
	v_rcp_f32_e32 v61, v57
	s_nop 0
	v_pk_mul_f32 v[60:61], v[62:63], v[60:61]
	s_nop 0
	v_pk_mul_f32 v[58:59], v[60:61], v[58:59]
	s_nop 0
	v_cvt_pk_bf16_f32 v57, v58, v59
	v_mul_f32_e32 v58, 0xbfb8aa3b, v52
	v_mul_f32_e32 v59, 0xbfb8aa3b, v53
	v_exp_f32_e32 v58, v58
	v_exp_f32_e32 v59, v59
	v_add_f32_e32 v58, 1.0, v58
	v_add_f32_e32 v59, 1.0, v59
	v_rcp_f32_e32 v58, v58
	v_rcp_f32_e32 v59, v59
	s_nop 0
	v_pk_mul_f32 v[52:53], v[52:53], v[58:59]
	s_nop 0
	v_pk_mul_f32 v[48:49], v[52:53], v[48:49]
	s_nop 0
	v_cvt_pk_bf16_f32 v58, v48, v49
	v_mul_f32_e32 v48, 0xbfb8aa3b, v54
	v_mul_f32_e32 v49, 0xbfb8aa3b, v55
	v_exp_f32_e32 v48, v48
	v_exp_f32_e32 v49, v49
	v_add_f32_e32 v48, 1.0, v48
	v_add_f32_e32 v49, 1.0, v49
	v_rcp_f32_e32 v48, v48
	v_rcp_f32_e32 v49, v49
	s_nop 0
	v_pk_mul_f32 v[48:49], v[54:55], v[48:49]
	s_nop 0
	v_pk_mul_f32 v[48:49], v[48:49], v[50:51]
	v_mul_f32_e32 v50, 0xbfb8aa3b, v44
	v_mul_f32_e32 v51, 0xbfb8aa3b, v45
	v_exp_f32_e32 v50, v50
	v_exp_f32_e32 v51, v51
	v_cvt_pk_bf16_f32 v59, v48, v49
	v_add_u32_e32 v48, 0x90, v146
	v_add_f32_e32 v50, 1.0, v50
	v_add_f32_e32 v51, 1.0, v51
	v_rcp_f32_e32 v50, v50
	v_rcp_f32_e32 v51, v51
; __device__ __forceinline__ unsigned cvtpk(float lo, float hi) { const f32x2 v = (f32x2){lo, hi}; const bf16v2 b = __builtin_convertvector(v, bf16v2); return __builtin_bit_cast(unsigned, b); }
; __device__ __forceinline__ float siluf_(float x) { return x * sigmoidf_(x); }
; #define PG8_WAIT_V(n) asm volatile("s_waitcnt vmcnt(" #n ")" ::: "memory")
; #define PG8_BAR __builtin_amdgcn_s_barrier()
; template <class Epi, class Sched>
; __device__ __forceinline__ void gemm_phase(PG8_LAS unsigned char* lds, const Gemm g, const Sched& S, const Epi& E) {
;     ...
;         if (!has_next) break;
; #pragma unroll
;         for (int a = 0; a < 2; ++a)
; #pragma unroll
;             for (int b = 0; b < 2; ++b)
; #pragma unroll
;                 for (int m = 0; m < 4; ++m)
; #pragma unroll
;                     for (int n = 0; n < 2; ++n) acc[a][b][m][n] = (f32x4){0.f, 0.f, 0.f, 0.f};
;         cur = nxt; cA = nA; cB = nB; ++ui;
;     }
;     PG8_WAIT_V(0);
;     if (wr == 0) PG8_BAR;
;     PG8_BAR;
;     __device__ __forceinline__ void operator()(const f32x4 (&acc)[2][2][4][2], const pg8::Unit& u, int wr, int wc, int fr, int fq) const {
;     ...
; #pragma unroll
;         for (int ai = 0; ai < 2; ++ai)
; #pragma unroll
;             for (int m = 0; m < 4; ++m) { bf16_t* rowp = O + (size_t)(row0 + ai * 128 + m * 16) * ldc + col0;
;                 const f32x4 g0 = acc[ai][0][m][0], g1 = acc[ai][0][m][1], u0 = acc[ai][1][m][0], u1 = acc[ai][1][m][1];
;                 u32x4 w; w.x = cvtpk(siluf_(g0[0]) * u0[0], siluf_(g0[1]) * u0[1]); w.y = cvtpk(siluf_(g0[2]) * u0[2], siluf_(g0[3]) * u0[3]);
;                 w.z = cvtpk(siluf_(g1[0]) * u1[0], siluf_(g1[1]) * u1[1]); w.w = cvtpk(siluf_(g1[2]) * u1[2], siluf_(g1[3]) * u1[3]);
;                 *(u32x4*)rowp = w; }
	v_mad_i64_i32 v[48:49], s[12:13], v48, s81, v[138:139]
	v_lshl_add_u64 v[48:49], v[48:49], 0, v[140:141]
	v_pk_mul_f32 v[44:45], v[44:45], v[50:51]
	global_store_dwordx4 v[64:65], v[56:59], off
	v_pk_mul_f32 v[40:41], v[44:45], v[40:41]
	s_nop 0
	v_cvt_pk_bf16_f32 v40, v40, v41
	v_mul_f32_e32 v41, 0xbfb8aa3b, v46
	v_exp_f32_e32 v41, v41
	s_nop 0
	v_add_f32_e32 v41, 1.0, v41
	v_rcp_f32_e32 v44, v41
	v_mul_f32_e32 v41, 0xbfb8aa3b, v47
	v_exp_f32_e32 v41, v41
	s_nop 0
	v_add_f32_e32 v41, 1.0, v41
	v_rcp_f32_e32 v45, v41
	s_nop 0
	v_pk_mul_f32 v[44:45], v[46:47], v[44:45]
	s_nop 0
	v_pk_mul_f32 v[42:43], v[44:45], v[42:43]
	s_nop 0
	v_cvt_pk_bf16_f32 v41, v42, v43
	v_mul_f32_e32 v42, 0xbfb8aa3b, v36
	v_mul_f32_e32 v43, 0xbfb8aa3b, v37
	v_exp_f32_e32 v42, v42
	v_exp_f32_e32 v43, v43
	v_add_f32_e32 v42, 1.0, v42
	v_add_f32_e32 v43, 1.0, v43
	v_rcp_f32_e32 v42, v42
	v_rcp_f32_e32 v43, v43
	s_nop 0
	v_pk_mul_f32 v[36:37], v[36:37], v[42:43]
	s_nop 0
	v_pk_mul_f32 v[32:33], v[36:37], v[32:33]
	s_nop 0
	v_cvt_pk_bf16_f32 v42, v32, v33
	v_mul_f32_e32 v32, 0xbfb8aa3b, v38
	v_mul_f32_e32 v33, 0xbfb8aa3b, v39
	v_exp_f32_e32 v32, v32
	v_exp_f32_e32 v33, v33
	v_add_f32_e32 v32, 1.0, v32
	v_add_f32_e32 v33, 1.0, v33
	v_rcp_f32_e32 v32, v32
	v_rcp_f32_e32 v33, v33
	s_nop 0
	v_pk_mul_f32 v[32:33], v[38:39], v[32:33]
	s_nop 0
	v_pk_mul_f32 v[32:33], v[32:33], v[34:35]
	v_mul_f32_e32 v34, 0xbfb8aa3b, v28
	v_mul_f32_e32 v35, 0xbfb8aa3b, v29
	v_exp_f32_e32 v34, v34
	v_exp_f32_e32 v35, v35
	v_cvt_pk_bf16_f32 v43, v32, v33
	v_add_u32_e32 v32, 0xa0, v146
	v_add_f32_e32 v34, 1.0, v34
	v_add_f32_e32 v35, 1.0, v35
	v_rcp_f32_e32 v34, v34
	v_rcp_f32_e32 v35, v35
	v_mad_i64_i32 v[32:33], s[12:13], v32, s81, v[138:139]
	v_lshl_add_u64 v[32:33], v[32:33], 0, v[140:141]
	v_pk_mul_f32 v[28:29], v[28:29], v[34:35]
	global_store_dwordx4 v[48:49], v[40:43], off
	v_pk_mul_f32 v[24:25], v[28:29], v[24:25]
	s_nop 0
	v_cvt_pk_bf16_f32 v24, v24, v25
	v_mul_f32_e32 v25, 0xbfb8aa3b, v30
	v_exp_f32_e32 v25, v25
	s_nop 0
	v_add_f32_e32 v25, 1.0, v25
	v_rcp_f32_e32 v28, v25
	v_mul_f32_e32 v25, 0xbfb8aa3b, v31
	v_exp_f32_e32 v25, v25
	s_nop 0
	v_add_f32_e32 v25, 1.0, v25
	v_rcp_f32_e32 v29, v25
	s_nop 0
	v_pk_mul_f32 v[28:29], v[30:31], v[28:29]
	s_nop 0
	v_pk_mul_f32 v[26:27], v[28:29], v[26:27]
	s_nop 0
	v_cvt_pk_bf16_f32 v25, v26, v27
	v_mul_f32_e32 v26, 0xbfb8aa3b, v20
	v_mul_f32_e32 v27, 0xbfb8aa3b, v21
	v_exp_f32_e32 v26, v26
	v_exp_f32_e32 v27, v27
	v_add_f32_e32 v26, 1.0, v26
	v_add_f32_e32 v27, 1.0, v27
	v_rcp_f32_e32 v26, v26
	v_rcp_f32_e32 v27, v27
	s_nop 0
	v_pk_mul_f32 v[20:21], v[20:21], v[26:27]
	s_nop 0
	v_pk_mul_f32 v[16:17], v[20:21], v[16:17]
	s_nop 0
	v_cvt_pk_bf16_f32 v26, v16, v17
	v_mul_f32_e32 v16, 0xbfb8aa3b, v22
	v_mul_f32_e32 v17, 0xbfb8aa3b, v23
	v_exp_f32_e32 v16, v16
	v_exp_f32_e32 v17, v17
	v_add_f32_e32 v16, 1.0, v16
	v_add_f32_e32 v17, 1.0, v17
	v_rcp_f32_e32 v16, v16
	v_rcp_f32_e32 v17, v17
	s_nop 0
	v_pk_mul_f32 v[16:17], v[22:23], v[16:17]
	s_nop 0
	v_pk_mul_f32 v[16:17], v[16:17], v[18:19]
	v_mul_f32_e32 v18, 0xbfb8aa3b, v12
	v_mul_f32_e32 v19, 0xbfb8aa3b, v13
	v_exp_f32_e32 v18, v18
	v_exp_f32_e32 v19, v19
	v_cvt_pk_bf16_f32 v27, v16, v17
	v_add_u32_e32 v16, 0xb0, v146
	v_add_f32_e32 v18, 1.0, v18
	v_add_f32_e32 v19, 1.0, v19
	v_rcp_f32_e32 v18, v18
	v_rcp_f32_e32 v19, v19
	v_mad_i64_i32 v[16:17], s[12:13], v16, s81, v[138:139]
	v_lshl_add_u64 v[16:17], v[16:17], 0, v[140:141]
	v_pk_mul_f32 v[12:13], v[12:13], v[18:19]
	s_mov_b64 s[12:13], s[6:7]
	v_pk_mul_f32 v[8:9], v[12:13], v[8:9]
	global_store_dwordx4 v[32:33], v[24:27], off
	v_cvt_pk_bf16_f32 v8, v8, v9
	v_mul_f32_e32 v9, 0xbfb8aa3b, v14
	v_exp_f32_e32 v9, v9
	s_nop 0
	v_add_f32_e32 v9, 1.0, v9
	v_rcp_f32_e32 v12, v9
	v_mul_f32_e32 v9, 0xbfb8aa3b, v15
	v_exp_f32_e32 v9, v9
	s_nop 0
	v_add_f32_e32 v9, 1.0, v9
	v_rcp_f32_e32 v13, v9
	s_nop 0
	v_pk_mul_f32 v[12:13], v[14:15], v[12:13]
	s_nop 0
	v_pk_mul_f32 v[10:11], v[12:13], v[10:11]
	s_nop 0
	v_cvt_pk_bf16_f32 v9, v10, v11
	v_mul_f32_e32 v10, 0xbfb8aa3b, v4
	v_mul_f32_e32 v11, 0xbfb8aa3b, v5
	v_exp_f32_e32 v10, v10
	v_exp_f32_e32 v11, v11
	v_add_f32_e32 v10, 1.0, v10
	v_add_f32_e32 v11, 1.0, v11
	v_rcp_f32_e32 v10, v10
	v_rcp_f32_e32 v11, v11
	s_nop 0
	v_pk_mul_f32 v[4:5], v[4:5], v[10:11]
	s_nop 0
	v_pk_mul_f32 v[0:1], v[4:5], v[0:1]
	s_nop 0
	v_cvt_pk_bf16_f32 v10, v0, v1
	v_mul_f32_e32 v0, 0xbfb8aa3b, v6
	v_mul_f32_e32 v1, 0xbfb8aa3b, v7
	v_exp_f32_e32 v0, v0
	v_exp_f32_e32 v1, v1
	v_add_f32_e32 v0, 1.0, v0
	v_add_f32_e32 v1, 1.0, v1
	v_rcp_f32_e32 v0, v0
	v_rcp_f32_e32 v1, v1
	s_nop 0
	v_pk_mul_f32 v[0:1], v[6:7], v[0:1]
	s_nop 0
	v_pk_mul_f32 v[0:1], v[0:1], v[2:3]
	s_nop 0
	v_cvt_pk_bf16_f32 v11, v0, v1
	global_store_dwordx4 v[16:17], v[8:11], off
	s_cbranch_vccz .LBB0_111
	s_waitcnt vmcnt(0)
	v_readlane_b32 s22, v255, 14
	s_cmpk_gt_u32 s19, 0xff
	v_readlane_b32 s23, v255, 15
	s_mov_b64 s[28:29], s[54:55]
	s_cbranch_scc1 .LBB0_118
	s_barrier

; #define PG8_STAGE(bufoff, gbase, voff) do { _Pragma("unroll") for (int _i = 0; _i < 2; ++_i) \
;         __builtin_amdgcn_global_load_lds((const unsigned*)((const char*)(gbase) + (voff)[_i]), (PG8_LAS unsigned*)(lds + (bufoff) + ldsw + _i * 8192), 16, 0, 0); } while (0)
; #define PG8_LDA(dst, b, h) do { _Pragma("unroll") for (int m = 0; m < 4; ++m) _Pragma("unroll") for (int k = 0; k < 2; ++k) dst[m][k] = *(const PG8_LAS bf16x8*)(lds + PG8_SA(b, h) + aoff + m * 2048 + k * 1024); } while (0)
; #define PG8_LDB(dst, b, h) do { _Pragma("unroll") for (int n = 0; n < 2; ++n) _Pragma("unroll") for (int k = 0; k < 2; ++k) dst[n][k] = *(const PG8_LAS bf16x8*)(lds + PG8_SB(b, h) + boff + n * 2048 + k * 1024); } while (0)
; #define PG8_MMA(ai, bj, At, Bt) do { __builtin_amdgcn_s_setprio(1); _Pragma("unroll") for (int m = 0; m < 4; ++m) _Pragma("unroll") for (int n = 0; n < 2; ++n) _Pragma("unroll") for (int k = 0; k < 2; ++k) \
;         acc[ai][bj][m][n] = __builtin_amdgcn_mfma_f32_16x16x32_bf16(Bt[n][k], At[m][k], acc[ai][bj][m][n], 0, 0, 0); __builtin_amdgcn_s_setprio(0); } while (0)
; #define PG8_WAIT_V(n) asm volatile("s_waitcnt vmcnt(" #n ")" ::: "memory")
; #define PG8_WAIT_L(n) asm volatile("s_waitcnt lgkmcnt(" #n ")" ::: "memory")
; #define PG8_BAR __builtin_amdgcn_s_barrier()
; #define PG8_SCHED __builtin_amdgcn_sched_barrier(0)
; template <class Epi, class Sched>
; __device__ __forceinline__ void gemm_phase(PG8_LAS unsigned char* lds, const Gemm g, const Sched& S, const Epi& E) {
;     ...
;             PG8_LDB(B0, 0, 0); PG8_SCHED; PG8_LDA(At, 0, 0); PG8_STAGE(PG8_SA(1, 1), a1 + hstep, voffA);
;             PG8_WAIT_L(8); PG8_BAR; PG8_WAIT_L(0); PG8_MMA(0, 0, At, B0); PG8_BAR; PG8_SCHED;
;             PG8_LDB(B1, 0, 1); PG8_STAGE(PG8_SB(0, 0), b2, voffB);
;             PG8_BAR; PG8_WAIT_L(0); PG8_MMA(0, 1, At, B1); PG8_BAR;
;             PG8_LDA(At, 0, 1); PG8_STAGE(PG8_SA(0, 0), a2, voffA);
;             PG8_BAR; PG8_WAIT_L(0); PG8_MMA(1, 0, At, B0); PG8_BAR; PG8_SCHED;
;             PG8_STAGE(PG8_SB(0, 1), b2 + hstep, voffB);
;             PG8_WAIT_V(6); PG8_BAR; PG8_MMA(1, 1, At, B1); PG8_BAR;
.LBB0_137:
	s_add_u32 s14, s12, 0xfffc0080
	s_addc_u32 s15, s13, -1
	v_add_u32_e32 v154, 0x10000, v139
	ds_read_b128 v[142:145], v154
	ds_read_b128 v[146:149], v154 offset:1024
	ds_read_b128 v[150:153], v154 offset:2048
	ds_read_b128 v[154:157], v154 offset:3072
	s_cmp_eq_u32 s45, 12
	s_cselect_b32 s17, s7, s15
	s_cselect_b32 s16, s40, s14
	s_cselect_b32 s15, s5, s44
	s_cselect_b32 s14, s41, s43
	s_add_i32 m0, s1, 0xc000
	ds_read_b128 v[158:161], v141
	ds_read_b128 v[162:165], v141 offset:1024
	ds_read_b128 v[166:169], v141 offset:2048
	ds_read_b128 v[170:173], v141 offset:3072
	ds_read_b128 v[178:181], v141 offset:4096
	ds_read_b128 v[182:185], v141 offset:5120
	ds_read_b128 v[186:189], v141 offset:6144
	ds_read_b128 v[190:193], v141 offset:7168
	global_load_lds_dwordx4 v134, s[12:13]
	s_add_i32 m0, s1, 0xe000
	s_nop 0
	global_load_lds_dwordx4 v136, s[12:13]
	s_waitcnt lgkmcnt(8)
	s_barrier
	s_waitcnt lgkmcnt(0)
	v_mfma_f32_16x16x32_bf16 v[124:127], v[142:145], v[158:161], v[124:127]
	v_mfma_f32_16x16x32_bf16 v[120:123], v[150:153], v[158:161], v[120:123]
	v_mfma_f32_16x16x32_bf16 v[116:119], v[142:145], v[166:169], v[116:119]
	v_mfma_f32_16x16x32_bf16 v[112:115], v[150:153], v[166:169], v[112:115]
	v_mfma_f32_16x16x32_bf16 v[100:103], v[142:145], v[178:181], v[100:103]
	v_mfma_f32_16x16x32_bf16 v[96:99], v[150:153], v[178:181], v[96:99]
	v_mfma_f32_16x16x32_bf16 v[84:87], v[142:145], v[186:189], v[84:87]
	v_mfma_f32_16x16x32_bf16 v[80:83], v[150:153], v[186:189], v[80:83]
	v_mfma_f32_16x16x32_bf16 v[124:127], v[146:149], v[162:165], v[124:127]
	v_mfma_f32_16x16x32_bf16 v[120:123], v[154:157], v[162:165], v[120:123]
	v_mfma_f32_16x16x32_bf16 v[116:119], v[146:149], v[170:173], v[116:119]
	v_mfma_f32_16x16x32_bf16 v[112:115], v[154:157], v[170:173], v[112:115]
	v_mfma_f32_16x16x32_bf16 v[100:103], v[146:149], v[182:185], v[100:103]
	v_mfma_f32_16x16x32_bf16 v[96:99], v[154:157], v[182:185], v[96:99]
	v_mfma_f32_16x16x32_bf16 v[84:87], v[146:149], v[190:193], v[84:87]
	v_mfma_f32_16x16x32_bf16 v[80:83], v[154:157], v[190:193], v[80:83]
	s_barrier
	s_add_i32 s48, 0, 0x14000
	v_add_u32_e32 v174, 0x14000, v139
	ds_read_b128 v[194:197], v174
	ds_read_b128 v[198:201], v174 offset:1024
	ds_read_b128 v[202:205], v174 offset:2048
	ds_read_b128 v[206:209], v174 offset:3072
	s_add_u32 s98, s14, 0x80
	s_addc_u32 s99, s15, 0
	s_add_i32 m0, s20, 0x10000
	s_nop 0
	global_load_lds_dwordx4 v176, s[14:15]
	s_add_i32 m0, s20, 0x12000
	s_nop 0
	global_load_lds_dwordx4 v128, s[14:15]
	s_barrier
	s_waitcnt lgkmcnt(0)
	v_mfma_f32_16x16x32_bf16 v[108:111], v[194:197], v[158:161], v[108:111]
	v_mfma_f32_16x16x32_bf16 v[104:107], v[202:205], v[158:161], v[104:107]
	v_mfma_f32_16x16x32_bf16 v[92:95], v[194:197], v[166:169], v[92:95]
	v_mfma_f32_16x16x32_bf16 v[88:91], v[202:205], v[166:169], v[88:91]
	v_mfma_f32_16x16x32_bf16 v[76:79], v[194:197], v[178:181], v[76:79]
	v_mfma_f32_16x16x32_bf16 v[72:75], v[202:205], v[178:181], v[72:75]
	v_mfma_f32_16x16x32_bf16 v[68:71], v[194:197], v[186:189], v[68:71]
	v_mfma_f32_16x16x32_bf16 v[64:67], v[202:205], v[186:189], v[64:67]
	v_mfma_f32_16x16x32_bf16 v[108:111], v[198:201], v[162:165], v[108:111]
	v_mfma_f32_16x16x32_bf16 v[104:107], v[206:209], v[162:165], v[104:107]
	v_mfma_f32_16x16x32_bf16 v[92:95], v[198:201], v[170:173], v[92:95]
	v_mfma_f32_16x16x32_bf16 v[88:91], v[206:209], v[170:173], v[88:91]
	v_mfma_f32_16x16x32_bf16 v[76:79], v[198:201], v[182:185], v[76:79]
	v_mfma_f32_16x16x32_bf16 v[72:75], v[206:209], v[182:185], v[72:75]
	v_mfma_f32_16x16x32_bf16 v[68:71], v[198:201], v[190:193], v[68:71]
	v_mfma_f32_16x16x32_bf16 v[64:67], v[206:209], v[190:193], v[64:67]
	s_mov_b32 m0, s1
	s_add_u32 s100, s16, 0x80
	s_addc_u32 s101, s17, 0
	s_barrier
	ds_read_b128 v[158:161], v141 offset:16384
	ds_read_b128 v[162:165], v141 offset:17408
	ds_read_b128 v[166:169], v141 offset:18432
	ds_read_b128 v[170:173], v141 offset:19456
	ds_read_b128 v[178:181], v141 offset:20480
	ds_read_b128 v[182:185], v141 offset:21504
	ds_read_b128 v[186:189], v141 offset:22528
	ds_read_b128 v[190:193], v141 offset:23552
	global_load_lds_dwordx4 v132, s[16:17]
	s_mov_b32 m0, s22
	s_nop 0
	global_load_lds_dwordx4 v130, s[16:17]
	s_barrier
	s_waitcnt lgkmcnt(0)
	v_mfma_f32_16x16x32_bf16 v[60:63], v[142:145], v[158:161], v[60:63]
	v_mfma_f32_16x16x32_bf16 v[56:59], v[150:153], v[158:161], v[56:59]
	v_mfma_f32_16x16x32_bf16 v[52:55], v[142:145], v[166:169], v[52:55]
	v_mfma_f32_16x16x32_bf16 v[48:51], v[150:153], v[166:169], v[48:51]
	v_mfma_f32_16x16x32_bf16 v[36:39], v[142:145], v[178:181], v[36:39]
	v_mfma_f32_16x16x32_bf16 v[32:35], v[150:153], v[178:181], v[32:35]
	v_mfma_f32_16x16x32_bf16 v[20:23], v[142:145], v[186:189], v[20:23]
	v_mfma_f32_16x16x32_bf16 v[16:19], v[150:153], v[186:189], v[16:19]
	v_mfma_f32_16x16x32_bf16 v[60:63], v[146:149], v[162:165], v[60:63]
	v_mfma_f32_16x16x32_bf16 v[56:59], v[154:157], v[162:165], v[56:59]
	v_mfma_f32_16x16x32_bf16 v[52:55], v[146:149], v[170:173], v[52:55]
	v_mfma_f32_16x16x32_bf16 v[48:51], v[154:157], v[170:173], v[48:51]
	v_mfma_f32_16x16x32_bf16 v[36:39], v[146:149], v[182:185], v[36:39]
	v_mfma_f32_16x16x32_bf16 v[32:35], v[154:157], v[182:185], v[32:35]
	v_mfma_f32_16x16x32_bf16 v[20:23], v[146:149], v[190:193], v[20:23]
	v_mfma_f32_16x16x32_bf16 v[16:19], v[154:157], v[190:193], v[16:19]
	s_barrier
	s_add_u32 s46, s14, 0x40000
	s_addc_u32 s47, s15, 0
	s_add_i32 m0, s20, 0x14000
	s_nop 0
	global_load_lds_dwordx4 v176, s[46:47]
	s_add_i32 m0, s20, 0x16000
	s_nop 0
	global_load_lds_dwordx4 v128, s[46:47]
	s_waitcnt vmcnt(6)
	s_barrier
; #define PG8_STAGE(bufoff, gbase, voff) do { _Pragma("unroll") for (int _i = 0; _i < 2; ++_i) \
;         __builtin_amdgcn_global_load_lds((const unsigned*)((const char*)(gbase) + (voff)[_i]), (PG8_LAS unsigned*)(lds + (bufoff) + ldsw + _i * 8192), 16, 0, 0); } while (0)
; #define PG8_LDA(dst, b, h) do { _Pragma("unroll") for (int m = 0; m < 4; ++m) _Pragma("unroll") for (int k = 0; k < 2; ++k) dst[m][k] = *(const PG8_LAS bf16x8*)(lds + PG8_SA(b, h) + aoff + m * 2048 + k * 1024); } while (0)
; #define PG8_LDB(dst, b, h) do { _Pragma("unroll") for (int n = 0; n < 2; ++n) _Pragma("unroll") for (int k = 0; k < 2; ++k) dst[n][k] = *(const PG8_LAS bf16x8*)(lds + PG8_SB(b, h) + boff + n * 2048 + k * 1024); } while (0)
; #define PG8_MMA(ai, bj, At, Bt) do { __builtin_amdgcn_s_setprio(1); _Pragma("unroll") for (int m = 0; m < 4; ++m) _Pragma("unroll") for (int n = 0; n < 2; ++n) _Pragma("unroll") for (int k = 0; k < 2; ++k) \
;         acc[ai][bj][m][n] = __builtin_amdgcn_mfma_f32_16x16x32_bf16(Bt[n][k], At[m][k], acc[ai][bj][m][n], 0, 0, 0); __builtin_amdgcn_s_setprio(0); } while (0)
; #define PG8_WAIT_V(n) asm volatile("s_waitcnt vmcnt(" #n ")" ::: "memory")
; #define PG8_WAIT_L(n) asm volatile("s_waitcnt lgkmcnt(" #n ")" ::: "memory")
; #define PG8_BAR __builtin_amdgcn_s_barrier()
; #define PG8_SCHED __builtin_amdgcn_sched_barrier(0)
; template <class Epi, class Sched>
; __device__ __forceinline__ void gemm_phase(PG8_LAS unsigned char* lds, const Gemm g, const Sched& S, const Epi& E) {
;     ...
;             PG8_WAIT_V(6); PG8_BAR; PG8_MMA(1, 1, At, B1); PG8_BAR;
;             PG8_LDB(B0, 1, 0); PG8_SCHED; PG8_LDA(At, 1, 0); PG8_STAGE(PG8_SA(0, 1), a2 + hstep, voffA);
;             PG8_WAIT_L(8); PG8_BAR; PG8_WAIT_L(0); PG8_MMA(0, 0, At, B0); PG8_BAR; PG8_SCHED;
;             PG8_LDB(B1, 1, 1); PG8_STAGE(PG8_SB(1, 0), b3, voffB);
;             PG8_BAR; PG8_WAIT_L(0); PG8_MMA(0, 1, At, B1); PG8_BAR;
;             PG8_LDA(At, 1, 1); PG8_STAGE(PG8_SA(1, 0), a3, voffA);
;             PG8_BAR; PG8_WAIT_L(0); PG8_MMA(1, 0, At, B0); PG8_BAR; PG8_SCHED;
	v_mfma_f32_16x16x32_bf16 v[44:47], v[194:197], v[158:161], v[44:47]
	v_mfma_f32_16x16x32_bf16 v[40:43], v[202:205], v[158:161], v[40:43]
	v_mfma_f32_16x16x32_bf16 v[28:31], v[194:197], v[166:169], v[28:31]
	v_mfma_f32_16x16x32_bf16 v[24:27], v[202:205], v[166:169], v[24:27]
	v_mfma_f32_16x16x32_bf16 v[12:15], v[194:197], v[178:181], v[12:15]
	v_mfma_f32_16x16x32_bf16 v[8:11], v[202:205], v[178:181], v[8:11]
	v_mfma_f32_16x16x32_bf16 v[4:7], v[194:197], v[186:189], v[4:7]
	v_mfma_f32_16x16x32_bf16 v[0:3], v[202:205], v[186:189], v[0:3]
	v_mfma_f32_16x16x32_bf16 v[44:47], v[198:201], v[162:165], v[44:47]
	v_mfma_f32_16x16x32_bf16 v[40:43], v[206:209], v[162:165], v[40:43]
	v_mfma_f32_16x16x32_bf16 v[28:31], v[198:201], v[170:173], v[28:31]
	v_mfma_f32_16x16x32_bf16 v[24:27], v[206:209], v[170:173], v[24:27]
	v_mfma_f32_16x16x32_bf16 v[12:15], v[198:201], v[182:185], v[12:15]
	v_mfma_f32_16x16x32_bf16 v[8:11], v[206:209], v[182:185], v[8:11]
	v_mfma_f32_16x16x32_bf16 v[4:7], v[198:201], v[190:193], v[4:7]
	v_mfma_f32_16x16x32_bf16 v[0:3], v[206:209], v[190:193], v[0:3]
	v_add_u32_e32 v154, 0x18000, v139
	s_barrier
	ds_read_b128 v[142:145], v154
	ds_read_b128 v[146:149], v154 offset:1024
	ds_read_b128 v[150:153], v154 offset:2048
	ds_read_b128 v[154:157], v154 offset:3072
	s_add_u32 s16, s16, 0x40000
	s_addc_u32 s17, s17, 0
	s_mov_b32 m0, s23
	ds_read_b128 v[158:161], v141 offset:32768
	ds_read_b128 v[162:165], v141 offset:33792
	ds_read_b128 v[166:169], v141 offset:34816
	ds_read_b128 v[170:173], v141 offset:35840
	ds_read_b128 v[178:181], v141 offset:36864
	ds_read_b128 v[182:185], v141 offset:37888
	ds_read_b128 v[186:189], v141 offset:38912
	ds_read_b128 v[190:193], v141 offset:39936
	global_load_lds_dwordx4 v132, s[16:17]
	s_mov_b32 m0, s26
	s_nop 0
	global_load_lds_dwordx4 v130, s[16:17]
	s_waitcnt lgkmcnt(8)
	s_barrier
	s_waitcnt lgkmcnt(0)
	v_mfma_f32_16x16x32_bf16 v[124:127], v[142:145], v[158:161], v[124:127]
	v_mfma_f32_16x16x32_bf16 v[120:123], v[150:153], v[158:161], v[120:123]
	v_mfma_f32_16x16x32_bf16 v[116:119], v[142:145], v[166:169], v[116:119]
	v_mfma_f32_16x16x32_bf16 v[112:115], v[150:153], v[166:169], v[112:115]
	v_mfma_f32_16x16x32_bf16 v[100:103], v[142:145], v[178:181], v[100:103]
	v_mfma_f32_16x16x32_bf16 v[96:99], v[150:153], v[178:181], v[96:99]
	v_mfma_f32_16x16x32_bf16 v[84:87], v[142:145], v[186:189], v[84:87]
	v_mfma_f32_16x16x32_bf16 v[80:83], v[150:153], v[186:189], v[80:83]
	v_mfma_f32_16x16x32_bf16 v[124:127], v[146:149], v[162:165], v[124:127]
	v_mfma_f32_16x16x32_bf16 v[120:123], v[154:157], v[162:165], v[120:123]
	v_mfma_f32_16x16x32_bf16 v[116:119], v[146:149], v[170:173], v[116:119]
	v_mfma_f32_16x16x32_bf16 v[112:115], v[154:157], v[170:173], v[112:115]
	v_mfma_f32_16x16x32_bf16 v[100:103], v[146:149], v[182:185], v[100:103]
	v_mfma_f32_16x16x32_bf16 v[96:99], v[154:157], v[182:185], v[96:99]
	v_mfma_f32_16x16x32_bf16 v[84:87], v[146:149], v[190:193], v[84:87]
	v_mfma_f32_16x16x32_bf16 v[80:83], v[154:157], v[190:193], v[80:83]
	s_barrier
	v_add_u32_e32 v206, 0x1c000, v139
	s_add_i32 m0, s20, 0x18000
	ds_read_b128 v[194:197], v206
	ds_read_b128 v[198:201], v206 offset:1024
	ds_read_b128 v[202:205], v206 offset:2048
	ds_read_b128 v[206:209], v206 offset:3072
	global_load_lds_dwordx4 v176, s[98:99]
	s_add_i32 m0, s20, 0x1a000
	s_nop 0
	global_load_lds_dwordx4 v128, s[98:99]
	s_barrier
	s_waitcnt lgkmcnt(0)
	v_mfma_f32_16x16x32_bf16 v[108:111], v[194:197], v[158:161], v[108:111]
	v_mfma_f32_16x16x32_bf16 v[104:107], v[202:205], v[158:161], v[104:107]
	v_mfma_f32_16x16x32_bf16 v[92:95], v[194:197], v[166:169], v[92:95]
	v_mfma_f32_16x16x32_bf16 v[88:91], v[202:205], v[166:169], v[88:91]
	v_mfma_f32_16x16x32_bf16 v[76:79], v[194:197], v[178:181], v[76:79]
	v_mfma_f32_16x16x32_bf16 v[72:75], v[202:205], v[178:181], v[72:75]
	v_mfma_f32_16x16x32_bf16 v[68:71], v[194:197], v[186:189], v[68:71]
	v_mfma_f32_16x16x32_bf16 v[64:67], v[202:205], v[186:189], v[64:67]
	v_mfma_f32_16x16x32_bf16 v[108:111], v[198:201], v[162:165], v[108:111]
	v_mfma_f32_16x16x32_bf16 v[104:107], v[206:209], v[162:165], v[104:107]
	v_mfma_f32_16x16x32_bf16 v[92:95], v[198:201], v[170:173], v[92:95]
	v_mfma_f32_16x16x32_bf16 v[88:91], v[206:209], v[170:173], v[88:91]
	v_mfma_f32_16x16x32_bf16 v[76:79], v[198:201], v[182:185], v[76:79]
	v_mfma_f32_16x16x32_bf16 v[72:75], v[206:209], v[182:185], v[72:75]
	v_mfma_f32_16x16x32_bf16 v[68:71], v[198:201], v[190:193], v[68:71]
	v_mfma_f32_16x16x32_bf16 v[64:67], v[206:209], v[190:193], v[64:67]
	s_mov_b32 m0, s28
	s_barrier
	ds_read_b128 v[158:161], v141 offset:49152
	ds_read_b128 v[162:165], v141 offset:50176
	ds_read_b128 v[166:169], v141 offset:51200
	ds_read_b128 v[170:173], v141 offset:52224
	ds_read_b128 v[178:181], v141 offset:53248
	ds_read_b128 v[182:185], v141 offset:54272
	ds_read_b128 v[186:189], v141 offset:55296
	ds_read_b128 v[190:193], v141 offset:56320
	global_load_lds_dwordx4 v132, s[100:101]
	s_mov_b32 m0, s29
	s_nop 0
	global_load_lds_dwordx4 v130, s[100:101]
	s_barrier
	s_waitcnt lgkmcnt(0)
	v_mfma_f32_16x16x32_bf16 v[60:63], v[142:145], v[158:161], v[60:63]
	v_mfma_f32_16x16x32_bf16 v[56:59], v[150:153], v[158:161], v[56:59]
	v_mfma_f32_16x16x32_bf16 v[52:55], v[142:145], v[166:169], v[52:55]
	v_mfma_f32_16x16x32_bf16 v[48:51], v[150:153], v[166:169], v[48:51]
	v_mfma_f32_16x16x32_bf16 v[36:39], v[142:145], v[178:181], v[36:39]
	v_mfma_f32_16x16x32_bf16 v[32:35], v[150:153], v[178:181], v[32:35]
	v_mfma_f32_16x16x32_bf16 v[20:23], v[142:145], v[186:189], v[20:23]
	v_mfma_f32_16x16x32_bf16 v[16:19], v[150:153], v[186:189], v[16:19]
	v_mfma_f32_16x16x32_bf16 v[60:63], v[146:149], v[162:165], v[60:63]
	v_mfma_f32_16x16x32_bf16 v[56:59], v[154:157], v[162:165], v[56:59]
	v_mfma_f32_16x16x32_bf16 v[52:55], v[146:149], v[170:173], v[52:55]
	v_mfma_f32_16x16x32_bf16 v[48:51], v[154:157], v[170:173], v[48:51]
	v_mfma_f32_16x16x32_bf16 v[36:39], v[146:149], v[182:185], v[36:39]
	v_mfma_f32_16x16x32_bf16 v[32:35], v[154:157], v[182:185], v[32:35]
	v_mfma_f32_16x16x32_bf16 v[20:23], v[146:149], v[190:193], v[20:23]
	v_mfma_f32_16x16x32_bf16 v[16:19], v[154:157], v[190:193], v[16:19]
	s_barrier
; __device__ __forceinline__ unsigned cvtpk(float lo, float hi) { const f32x2 v = (f32x2){lo, hi}; const bf16v2 b = __builtin_convertvector(v, bf16v2); return __builtin_bit_cast(unsigned, b); }
; #define PG8_STAGE(bufoff, gbase, voff) do { _Pragma("unroll") for (int _i = 0; _i < 2; ++_i) \
;         __builtin_amdgcn_global_load_lds((const unsigned*)((const char*)(gbase) + (voff)[_i]), (PG8_LAS unsigned*)(lds + (bufoff) + ldsw + _i * 8192), 16, 0, 0); } while (0)
; #define PG8_MMA(ai, bj, At, Bt) do { __builtin_amdgcn_s_setprio(1); _Pragma("unroll") for (int m = 0; m < 4; ++m) _Pragma("unroll") for (int n = 0; n < 2; ++n) _Pragma("unroll") for (int k = 0; k < 2; ++k) \
;         acc[ai][bj][m][n] = __builtin_amdgcn_mfma_f32_16x16x32_bf16(Bt[n][k], At[m][k], acc[ai][bj][m][n], 0, 0, 0); __builtin_amdgcn_s_setprio(0); } while (0)
; #define PG8_WAIT_V(n) asm volatile("s_waitcnt vmcnt(" #n ")" ::: "memory")
; #define PG8_BAR __builtin_amdgcn_s_barrier()
; template <class Epi, class Sched>
; __device__ __forceinline__ void gemm_phase(PG8_LAS unsigned char* lds, const Gemm g, const Sched& S, const Epi& E) {
;     ...
;             PG8_STAGE(PG8_SB(1, 1), b3 + hstep, voffB);
;             PG8_WAIT_V(6); PG8_BAR; PG8_MMA(1, 1, At, B1); PG8_BAR;
;         }
;     __device__ __forceinline__ void operator()(const f32x4 (&acc)[2][2][4][2], const pg8::Unit& u, int wr, int wc, int fr, int fq) const {
;         const int row0 = u.pm * 256 + wr * 64 + fr, col0 = u.pn * 256 + wc * 32 + 8 * fq;
; #pragma unroll
;         for (int ai = 0; ai < 2; ++ai)
; #pragma unroll
;             for (int m = 0; m < 4; ++m) { bf16_t* rowp = O + (size_t)(row0 + ai * 128 + m * 16) * ldc + col0;
; #pragma unroll
;                 for (int bj = 0; bj < 2; ++bj) { const f32x4 v0 = acc[ai][bj][m][0], v1 = acc[ai][bj][m][1];
;                     u32x4 w; w.x = cvtpk(v0[0], v0[1]); w.y = cvtpk(v0[2], v0[3]); w.z = cvtpk(v1[0], v1[1]); w.w = cvtpk(v1[2], v1[3]);
;                     *(u32x4*)(rowp + bj * 128) = w; } }
;     }
	s_add_u32 s14, s14, 0x40080
	s_addc_u32 s15, s15, 0
	s_add_i32 m0, s20, 0x1c000
	s_nop 0
	global_load_lds_dwordx4 v176, s[14:15]
	s_add_i32 m0, s20, 0x1e000
	s_nop 0
	global_load_lds_dwordx4 v128, s[14:15]
	s_waitcnt vmcnt(6)
	s_barrier
	v_mfma_f32_16x16x32_bf16 v[44:47], v[194:197], v[158:161], v[44:47]
	v_mfma_f32_16x16x32_bf16 v[40:43], v[202:205], v[158:161], v[40:43]
	v_mfma_f32_16x16x32_bf16 v[28:31], v[194:197], v[166:169], v[28:31]
	v_mfma_f32_16x16x32_bf16 v[24:27], v[202:205], v[166:169], v[24:27]
	v_mfma_f32_16x16x32_bf16 v[12:15], v[194:197], v[178:181], v[12:15]
	v_mfma_f32_16x16x32_bf16 v[8:11], v[202:205], v[178:181], v[8:11]
	v_mfma_f32_16x16x32_bf16 v[4:7], v[194:197], v[186:189], v[4:7]
	v_mfma_f32_16x16x32_bf16 v[0:3], v[202:205], v[186:189], v[0:3]
	v_mfma_f32_16x16x32_bf16 v[44:47], v[198:201], v[162:165], v[44:47]
	v_mfma_f32_16x16x32_bf16 v[40:43], v[206:209], v[162:165], v[40:43]
	v_mfma_f32_16x16x32_bf16 v[28:31], v[198:201], v[170:173], v[28:31]
	v_mfma_f32_16x16x32_bf16 v[24:27], v[206:209], v[170:173], v[24:27]
	v_mfma_f32_16x16x32_bf16 v[12:15], v[198:201], v[182:185], v[12:15]
	v_mfma_f32_16x16x32_bf16 v[8:11], v[206:209], v[182:185], v[8:11]
	v_mfma_f32_16x16x32_bf16 v[4:7], v[198:201], v[190:193], v[4:7]
	v_mfma_f32_16x16x32_bf16 v[0:3], v[206:209], v[190:193], v[0:3]
	s_add_i32 s45, s45, 2
	s_add_u32 s12, s12, 0x100
	s_addc_u32 s13, s13, 0
	s_add_u32 s43, s43, 0x100
	s_addc_u32 s44, s44, 0
	s_cmp_gt_u32 s45, 13
	s_barrier
	s_cbranch_scc0 .LBB0_137
	v_lshl_add_u32 v142, s0, 8, v138
	v_lshl_or_b32 v144, s34, 8, v140
	v_ashrrev_i32_e32 v143, 31, v142
	v_readlane_b32 s12, v253, 18
	v_ashrrev_i32_e32 v145, 31, v144
	v_lshlrev_b64 v[146:147], 11, v[142:143]
	v_readlane_b32 s13, v253, 19
	v_cvt_pk_bf16_f32 v108, v108, v109
	v_cvt_pk_bf16_f32 v109, v110, v111
	v_cvt_pk_bf16_f32 v110, v104, v105
	v_or_b32_e32 v104, 16, v142
	v_cvt_pk_bf16_f32 v92, v92, v93
	v_cvt_pk_bf16_f32 v93, v94, v95
	v_cvt_pk_bf16_f32 v94, v88, v89
	v_or_b32_e32 v88, 32, v142
	v_cvt_pk_bf16_f32 v76, v76, v77
	v_cvt_pk_bf16_f32 v77, v78, v79
	v_cvt_pk_bf16_f32 v78, v72, v73
	v_or_b32_e32 v72, 48, v142
	v_lshl_add_u64 v[146:147], s[12:13], 0, v[146:147]
	v_lshlrev_b64 v[144:145], 1, v[144:145]
	v_ashrrev_i32_e32 v105, 31, v104
	v_ashrrev_i32_e32 v89, 31, v88
	v_ashrrev_i32_e32 v73, 31, v72
	v_lshl_add_u64 v[146:147], v[146:147], 0, v[144:145]
	v_lshlrev_b64 v[104:105], 11, v[104:105]
	v_lshlrev_b64 v[88:89], 11, v[88:89]
	v_lshlrev_b64 v[72:73], 11, v[72:73]
	v_lshl_add_u64 v[104:105], s[12:13], 0, v[104:105]
	v_lshl_add_u64 v[88:89], s[12:13], 0, v[88:89]
	v_lshl_add_u64 v[72:73], s[12:13], 0, v[72:73]
	s_mov_b64 s[12:13], 0x40000
	v_cvt_pk_bf16_f32 v60, v60, v61
	v_cvt_pk_bf16_f32 v61, v62, v63
	v_cvt_pk_bf16_f32 v62, v56, v57
	v_add_co_u32_e32 v56, vcc, s2, v146
	v_cvt_pk_bf16_f32 v68, v68, v69
	v_cvt_pk_bf16_f32 v69, v70, v71
	v_cvt_pk_bf16_f32 v70, v64, v65
	v_lshl_add_u64 v[64:65], v[146:147], 0, s[12:13]
	v_addc_co_u32_e32 v57, vcc, 0, v147, vcc
	v_cvt_pk_bf16_f32 v44, v44, v45
	v_cvt_pk_bf16_f32 v45, v46, v47
	v_cvt_pk_bf16_f32 v46, v40, v41
	v_cvt_pk_bf16_f32 v47, v42, v43
	s_mov_b32 s0, 0x48000
	global_store_dwordx4 v[64:65], v[44:47], off offset:256
	s_mov_b64 s[12:13], 0x48000
	v_cvt_pk_bf16_f32 v28, v28, v29
	v_add_co_u32_e32 v46, vcc, s0, v146
	v_lshl_add_u64 v[44:45], v[146:147], 0, s[12:13]
	s_nop 0
	v_addc_co_u32_e32 v47, vcc, 0, v147, vcc
	v_cvt_pk_bf16_f32 v29, v30, v31
	v_cvt_pk_bf16_f32 v30, v24, v25
	v_cvt_pk_bf16_f32 v31, v26, v27
	s_mov_b32 s0, 0x50000
	global_store_dwordx4 v[44:45], v[28:31], off offset:256
	s_mov_b64 s[12:13], 0x50000
	v_cvt_pk_bf16_f32 v111, v106, v107
	v_add_co_u32_e32 v30, vcc, s0, v146
	v_lshl_add_u64 v[28:29], v[146:147], 0, s[12:13]
	s_nop 0
	v_addc_co_u32_e32 v31, vcc, 0, v147, vcc
	v_cvt_pk_bf16_f32 v12, v12, v13
	v_cvt_pk_bf16_f32 v13, v14, v15
	v_cvt_pk_bf16_f32 v14, v8, v9
	v_cvt_pk_bf16_f32 v15, v10, v11
	s_mov_b32 s0, 0x58000
	global_store_dwordx4 v[146:147], v[108:111], off offset:256
	v_cvt_pk_bf16_f32 v95, v90, v91
	global_store_dwordx4 v[28:29], v[12:15], off offset:256
	v_lshl_add_u64 v[108:109], v[104:105], 0, v[144:145]
	global_store_dwordx4 v[108:109], v[92:95], off offset:256
	v_add_co_u32_e32 v14, vcc, s0, v146
	s_nop 0
	v_lshl_add_u64 v[92:93], v[88:89], 0, v[144:145]
	v_cvt_pk_bf16_f32 v79, v74, v75
	s_mov_b64 s[12:13], 0x58000
	v_addc_co_u32_e32 v15, vcc, 0, v147, vcc
	v_cvt_pk_bf16_f32 v124, v124, v125
	v_cvt_pk_bf16_f32 v125, v126, v127
	v_cvt_pk_bf16_f32 v126, v120, v121
	v_cvt_pk_bf16_f32 v127, v122, v123
	v_cvt_pk_bf16_f32 v104, v116, v117
	v_cvt_pk_bf16_f32 v105, v118, v119
	v_cvt_pk_bf16_f32 v106, v112, v113
	v_cvt_pk_bf16_f32 v107, v114, v115
	v_cvt_pk_bf16_f32 v88, v100, v101
	v_cvt_pk_bf16_f32 v89, v102, v103
	v_cvt_pk_bf16_f32 v90, v96, v97
	v_cvt_pk_bf16_f32 v91, v98, v99
	global_store_dwordx4 v[92:93], v[76:79], off offset:256
	v_cvt_pk_bf16_f32 v74, v80, v81
	v_cvt_pk_bf16_f32 v75, v82, v83
	v_lshl_add_u64 v[76:77], v[72:73], 0, v[144:145]
	v_cvt_pk_bf16_f32 v72, v84, v85
	v_cvt_pk_bf16_f32 v73, v86, v87
	v_cvt_pk_bf16_f32 v71, v66, v67
	v_cvt_pk_bf16_f32 v63, v58, v59
	v_cvt_pk_bf16_f32 v40, v52, v53
	v_cvt_pk_bf16_f32 v41, v54, v55
	v_cvt_pk_bf16_f32 v42, v48, v49
	v_cvt_pk_bf16_f32 v43, v50, v51
	v_cvt_pk_bf16_f32 v24, v36, v37
	v_cvt_pk_bf16_f32 v25, v38, v39
	v_cvt_pk_bf16_f32 v26, v32, v33
	v_cvt_pk_bf16_f32 v27, v34, v35
	v_lshl_add_u64 v[12:13], v[146:147], 0, s[12:13]
	v_cvt_pk_bf16_f32 v8, v20, v21
	v_cvt_pk_bf16_f32 v9, v22, v23
	v_cvt_pk_bf16_f32 v10, v16, v17
	v_cvt_pk_bf16_f32 v11, v18, v19
	v_cvt_pk_bf16_f32 v4, v4, v5
	v_cvt_pk_bf16_f32 v5, v6, v7
	v_cvt_pk_bf16_f32 v6, v0, v1
	v_cvt_pk_bf16_f32 v7, v2, v3
	s_and_b64 vcc, exec, s[38:39]
	s_mov_b32 s34, s4
	s_mov_b32 s0, s6
	s_mov_b64 s[14:15], s[10:11]
	s_mov_b64 s[12:13], s[8:9]
	global_store_dwordx4 v[146:147], v[124:127], off
	global_store_dwordx4 v[108:109], v[104:107], off
	global_store_dwordx4 v[92:93], v[88:91], off
	global_store_dwordx4 v[76:77], v[72:75], off
	global_store_dwordx4 v[76:77], v[68:71], off offset:256
	global_store_dwordx4 v[56:57], v[60:63], off
	global_store_dwordx4 v[46:47], v[40:43], off
	global_store_dwordx4 v[30:31], v[24:27], off
	global_store_dwordx4 v[14:15], v[8:11], off
	global_store_dwordx4 v[12:13], v[4:7], off offset:256
	s_cbranch_vccz .LBB0_134
	s_waitcnt vmcnt(0)
	v_readlane_b32 s22, v255, 14
	s_cmpk_gt_u32 s19, 0xff
	v_readlane_b32 s23, v255, 15
	s_mov_b64 s[28:29], s[54:55]
	s_cbranch_scc1 .LBB0_141
	s_barrier

; #define PG8_STAGE(bufoff, gbase, voff) do { _Pragma("unroll") for (int _i = 0; _i < 2; ++_i) \
;         __builtin_amdgcn_global_load_lds((const unsigned*)((const char*)(gbase) + (voff)[_i]), (PG8_LAS unsigned*)(lds + (bufoff) + ldsw + _i * 8192), 16, 0, 0); } while (0)
; #define PG8_LDA(dst, b, h) do { _Pragma("unroll") for (int m = 0; m < 4; ++m) _Pragma("unroll") for (int k = 0; k < 2; ++k) dst[m][k] = *(const PG8_LAS bf16x8*)(lds + PG8_SA(b, h) + aoff + m * 2048 + k * 1024); } while (0)
; #define PG8_LDB(dst, b, h) do { _Pragma("unroll") for (int n = 0; n < 2; ++n) _Pragma("unroll") for (int k = 0; k < 2; ++k) dst[n][k] = *(const PG8_LAS bf16x8*)(lds + PG8_SB(b, h) + boff + n * 2048 + k * 1024); } while (0)
; #define PG8_MMA(ai, bj, At, Bt) do { __builtin_amdgcn_s_setprio(1); _Pragma("unroll") for (int m = 0; m < 4; ++m) _Pragma("unroll") for (int n = 0; n < 2; ++n) _Pragma("unroll") for (int k = 0; k < 2; ++k) \
;         acc[ai][bj][m][n] = __builtin_amdgcn_mfma_f32_16x16x32_bf16(Bt[n][k], At[m][k], acc[ai][bj][m][n], 0, 0, 0); __builtin_amdgcn_s_setprio(0); } while (0)
; #define PG8_WAIT_V(n) asm volatile("s_waitcnt vmcnt(" #n ")" ::: "memory")
; #define PG8_WAIT_L(n) asm volatile("s_waitcnt lgkmcnt(" #n ")" ::: "memory")
; #define PG8_BAR __builtin_amdgcn_s_barrier()
; #define PG8_SCHED __builtin_amdgcn_sched_barrier(0)
; template <class Epi, class Sched>
; __device__ __forceinline__ void gemm_phase(PG8_LAS unsigned char* lds, const Gemm g, const Sched& S, const Epi& E) {
;     ...
;             PG8_LDB(B0, 0, 0); PG8_SCHED; PG8_LDA(At, 0, 0); PG8_STAGE(PG8_SA(1, 1), a1 + hstep, voffA);
;             PG8_WAIT_L(8); PG8_BAR; PG8_WAIT_L(0); PG8_MMA(0, 0, At, B0); PG8_BAR; PG8_SCHED;
;             PG8_LDB(B1, 0, 1); PG8_STAGE(PG8_SB(0, 0), b2, voffB);
;             PG8_BAR; PG8_WAIT_L(0); PG8_MMA(0, 1, At, B1); PG8_BAR;
;             PG8_LDA(At, 0, 1); PG8_STAGE(PG8_SA(0, 0), a2, voffA);
;             PG8_BAR; PG8_WAIT_L(0); PG8_MMA(1, 0, At, B0); PG8_BAR; PG8_SCHED;
;             PG8_STAGE(PG8_SB(0, 1), b2 + hstep, voffB);
;             PG8_WAIT_V(6); PG8_BAR; PG8_MMA(1, 1, At, B1); PG8_BAR;
.LBB0_358:
	s_add_u32 s14, s12, 0xfffc0080
	s_addc_u32 s15, s13, -1
	v_add_u32_e32 v154, 0x10000, v139
	ds_read_b128 v[142:145], v154
	ds_read_b128 v[146:149], v154 offset:1024
	ds_read_b128 v[150:153], v154 offset:2048
	ds_read_b128 v[154:157], v154 offset:3072
	s_cmp_eq_u32 s45, 12
	s_cselect_b32 s17, s7, s15
	s_cselect_b32 s16, s40, s14
	s_cselect_b32 s15, s5, s44
	s_cselect_b32 s14, s41, s43
	s_add_i32 m0, s1, 0xc000
	ds_read_b128 v[158:161], v141
	ds_read_b128 v[162:165], v141 offset:1024
	ds_read_b128 v[166:169], v141 offset:2048
	ds_read_b128 v[170:173], v141 offset:3072
	ds_read_b128 v[182:185], v141 offset:4096
	ds_read_b128 v[190:193], v141 offset:5120
	ds_read_b128 v[194:197], v141 offset:6144
	ds_read_b128 v[198:201], v141 offset:7168
	global_load_lds_dwordx4 v134, s[12:13]
	s_add_i32 m0, s1, 0xe000
	s_nop 0
	global_load_lds_dwordx4 v136, s[12:13]
	s_waitcnt lgkmcnt(8)
	s_barrier
	s_waitcnt lgkmcnt(0)
	v_mfma_f32_16x16x32_bf16 v[124:127], v[142:145], v[158:161], v[124:127]
	v_mfma_f32_16x16x32_bf16 v[120:123], v[150:153], v[158:161], v[120:123]
	v_mfma_f32_16x16x32_bf16 v[116:119], v[142:145], v[166:169], v[116:119]
	v_mfma_f32_16x16x32_bf16 v[112:115], v[150:153], v[166:169], v[112:115]
	v_mfma_f32_16x16x32_bf16 v[100:103], v[142:145], v[182:185], v[100:103]
	v_mfma_f32_16x16x32_bf16 v[96:99], v[150:153], v[182:185], v[96:99]
	v_mfma_f32_16x16x32_bf16 v[84:87], v[142:145], v[194:197], v[84:87]
	v_mfma_f32_16x16x32_bf16 v[80:83], v[150:153], v[194:197], v[80:83]
	v_mfma_f32_16x16x32_bf16 v[124:127], v[146:149], v[162:165], v[124:127]
	v_mfma_f32_16x16x32_bf16 v[120:123], v[154:157], v[162:165], v[120:123]
	v_mfma_f32_16x16x32_bf16 v[116:119], v[146:149], v[170:173], v[116:119]
	v_mfma_f32_16x16x32_bf16 v[112:115], v[154:157], v[170:173], v[112:115]
	v_mfma_f32_16x16x32_bf16 v[100:103], v[146:149], v[190:193], v[100:103]
	v_mfma_f32_16x16x32_bf16 v[96:99], v[154:157], v[190:193], v[96:99]
	v_mfma_f32_16x16x32_bf16 v[84:87], v[146:149], v[198:201], v[84:87]
	v_mfma_f32_16x16x32_bf16 v[80:83], v[154:157], v[198:201], v[80:83]
	s_barrier
	s_add_i32 s48, 0, 0x14000
	v_add_u32_e32 v174, 0x14000, v139
	ds_read_b128 v[202:205], v174
	ds_read_b128 v[206:209], v174 offset:1024
	ds_read_b128 v[210:213], v174 offset:2048
	ds_read_b128 v[214:217], v174 offset:3072
	s_add_u32 s98, s14, 0x80
	s_addc_u32 s99, s15, 0
	s_add_i32 m0, s20, 0x10000
	s_nop 0
	global_load_lds_dwordx4 v176, s[14:15]
	s_add_i32 m0, s20, 0x12000
	s_nop 0
	global_load_lds_dwordx4 v128, s[14:15]
	s_barrier
	s_waitcnt lgkmcnt(0)
	v_mfma_f32_16x16x32_bf16 v[108:111], v[202:205], v[158:161], v[108:111]
	v_mfma_f32_16x16x32_bf16 v[104:107], v[210:213], v[158:161], v[104:107]
	v_mfma_f32_16x16x32_bf16 v[92:95], v[202:205], v[166:169], v[92:95]
	v_mfma_f32_16x16x32_bf16 v[88:91], v[210:213], v[166:169], v[88:91]
	v_mfma_f32_16x16x32_bf16 v[76:79], v[202:205], v[182:185], v[76:79]
	v_mfma_f32_16x16x32_bf16 v[72:75], v[210:213], v[182:185], v[72:75]
	v_mfma_f32_16x16x32_bf16 v[68:71], v[202:205], v[194:197], v[68:71]
	v_mfma_f32_16x16x32_bf16 v[64:67], v[210:213], v[194:197], v[64:67]
	v_mfma_f32_16x16x32_bf16 v[108:111], v[206:209], v[162:165], v[108:111]
	v_mfma_f32_16x16x32_bf16 v[104:107], v[214:217], v[162:165], v[104:107]
	v_mfma_f32_16x16x32_bf16 v[92:95], v[206:209], v[170:173], v[92:95]
	v_mfma_f32_16x16x32_bf16 v[88:91], v[214:217], v[170:173], v[88:91]
	v_mfma_f32_16x16x32_bf16 v[76:79], v[206:209], v[190:193], v[76:79]
	v_mfma_f32_16x16x32_bf16 v[72:75], v[214:217], v[190:193], v[72:75]
	v_mfma_f32_16x16x32_bf16 v[68:71], v[206:209], v[198:201], v[68:71]
	v_mfma_f32_16x16x32_bf16 v[64:67], v[214:217], v[198:201], v[64:67]
	s_mov_b32 m0, s1
	s_add_u32 s100, s16, 0x80
	s_addc_u32 s101, s17, 0
	s_barrier
	ds_read_b128 v[158:161], v141 offset:16384
	ds_read_b128 v[162:165], v141 offset:17408
	ds_read_b128 v[166:169], v141 offset:18432
	ds_read_b128 v[170:173], v141 offset:19456
	ds_read_b128 v[182:185], v141 offset:20480
	ds_read_b128 v[190:193], v141 offset:21504
	ds_read_b128 v[194:197], v141 offset:22528
	ds_read_b128 v[198:201], v141 offset:23552
	global_load_lds_dwordx4 v132, s[16:17]
	s_mov_b32 m0, s22
	s_nop 0
	global_load_lds_dwordx4 v130, s[16:17]
	s_barrier
	s_waitcnt lgkmcnt(0)
	v_mfma_f32_16x16x32_bf16 v[60:63], v[142:145], v[158:161], v[60:63]
	v_mfma_f32_16x16x32_bf16 v[56:59], v[150:153], v[158:161], v[56:59]
	v_mfma_f32_16x16x32_bf16 v[52:55], v[142:145], v[166:169], v[52:55]
	v_mfma_f32_16x16x32_bf16 v[48:51], v[150:153], v[166:169], v[48:51]
	v_mfma_f32_16x16x32_bf16 v[36:39], v[142:145], v[182:185], v[36:39]
	v_mfma_f32_16x16x32_bf16 v[32:35], v[150:153], v[182:185], v[32:35]
	v_mfma_f32_16x16x32_bf16 v[20:23], v[142:145], v[194:197], v[20:23]
	v_mfma_f32_16x16x32_bf16 v[16:19], v[150:153], v[194:197], v[16:19]
	v_mfma_f32_16x16x32_bf16 v[60:63], v[146:149], v[162:165], v[60:63]
	v_mfma_f32_16x16x32_bf16 v[56:59], v[154:157], v[162:165], v[56:59]
	v_mfma_f32_16x16x32_bf16 v[52:55], v[146:149], v[170:173], v[52:55]
	v_mfma_f32_16x16x32_bf16 v[48:51], v[154:157], v[170:173], v[48:51]
	v_mfma_f32_16x16x32_bf16 v[36:39], v[146:149], v[190:193], v[36:39]
	v_mfma_f32_16x16x32_bf16 v[32:35], v[154:157], v[190:193], v[32:35]
	v_mfma_f32_16x16x32_bf16 v[20:23], v[146:149], v[198:201], v[20:23]
	v_mfma_f32_16x16x32_bf16 v[16:19], v[154:157], v[198:201], v[16:19]
	s_barrier
	s_add_u32 s46, s14, 0x40000
	s_addc_u32 s47, s15, 0
	s_add_i32 m0, s20, 0x14000
	s_nop 0
	global_load_lds_dwordx4 v176, s[46:47]
	s_add_i32 m0, s20, 0x16000
	s_nop 0
	global_load_lds_dwordx4 v128, s[46:47]
	s_waitcnt vmcnt(6)
	s_barrier
; #define PG8_STAGE(bufoff, gbase, voff) do { _Pragma("unroll") for (int _i = 0; _i < 2; ++_i) \
;         __builtin_amdgcn_global_load_lds((const unsigned*)((const char*)(gbase) + (voff)[_i]), (PG8_LAS unsigned*)(lds + (bufoff) + ldsw + _i * 8192), 16, 0, 0); } while (0)
; #define PG8_LDA(dst, b, h) do { _Pragma("unroll") for (int m = 0; m < 4; ++m) _Pragma("unroll") for (int k = 0; k < 2; ++k) dst[m][k] = *(const PG8_LAS bf16x8*)(lds + PG8_SA(b, h) + aoff + m * 2048 + k * 1024); } while (0)
; #define PG8_LDB(dst, b, h) do { _Pragma("unroll") for (int n = 0; n < 2; ++n) _Pragma("unroll") for (int k = 0; k < 2; ++k) dst[n][k] = *(const PG8_LAS bf16x8*)(lds + PG8_SB(b, h) + boff + n * 2048 + k * 1024); } while (0)
; #define PG8_MMA(ai, bj, At, Bt) do { __builtin_amdgcn_s_setprio(1); _Pragma("unroll") for (int m = 0; m < 4; ++m) _Pragma("unroll") for (int n = 0; n < 2; ++n) _Pragma("unroll") for (int k = 0; k < 2; ++k) \
;         acc[ai][bj][m][n] = __builtin_amdgcn_mfma_f32_16x16x32_bf16(Bt[n][k], At[m][k], acc[ai][bj][m][n], 0, 0, 0); __builtin_amdgcn_s_setprio(0); } while (0)
; #define PG8_WAIT_V(n) asm volatile("s_waitcnt vmcnt(" #n ")" ::: "memory")
; #define PG8_WAIT_L(n) asm volatile("s_waitcnt lgkmcnt(" #n ")" ::: "memory")
; #define PG8_BAR __builtin_amdgcn_s_barrier()
; #define PG8_SCHED __builtin_amdgcn_sched_barrier(0)
; template <class Epi, class Sched>
; __device__ __forceinline__ void gemm_phase(PG8_LAS unsigned char* lds, const Gemm g, const Sched& S, const Epi& E) {
;     ...
;             PG8_WAIT_V(6); PG8_BAR; PG8_MMA(1, 1, At, B1); PG8_BAR;
;             PG8_LDB(B0, 1, 0); PG8_SCHED; PG8_LDA(At, 1, 0); PG8_STAGE(PG8_SA(0, 1), a2 + hstep, voffA);
;             PG8_WAIT_L(8); PG8_BAR; PG8_WAIT_L(0); PG8_MMA(0, 0, At, B0); PG8_BAR; PG8_SCHED;
;             PG8_LDB(B1, 1, 1); PG8_STAGE(PG8_SB(1, 0), b3, voffB);
;             PG8_BAR; PG8_WAIT_L(0); PG8_MMA(0, 1, At, B1); PG8_BAR;
;             PG8_LDA(At, 1, 1); PG8_STAGE(PG8_SA(1, 0), a3, voffA);
;             PG8_BAR; PG8_WAIT_L(0); PG8_MMA(1, 0, At, B0); PG8_BAR; PG8_SCHED;
	v_mfma_f32_16x16x32_bf16 v[44:47], v[202:205], v[158:161], v[44:47]
	v_mfma_f32_16x16x32_bf16 v[40:43], v[210:213], v[158:161], v[40:43]
	v_mfma_f32_16x16x32_bf16 v[28:31], v[202:205], v[166:169], v[28:31]
	v_mfma_f32_16x16x32_bf16 v[24:27], v[210:213], v[166:169], v[24:27]
	v_mfma_f32_16x16x32_bf16 v[12:15], v[202:205], v[182:185], v[12:15]
	v_mfma_f32_16x16x32_bf16 v[8:11], v[210:213], v[182:185], v[8:11]
	v_mfma_f32_16x16x32_bf16 v[4:7], v[202:205], v[194:197], v[4:7]
	v_mfma_f32_16x16x32_bf16 v[0:3], v[210:213], v[194:197], v[0:3]
	v_mfma_f32_16x16x32_bf16 v[44:47], v[206:209], v[162:165], v[44:47]
	v_mfma_f32_16x16x32_bf16 v[40:43], v[214:217], v[162:165], v[40:43]
	v_mfma_f32_16x16x32_bf16 v[28:31], v[206:209], v[170:173], v[28:31]
	v_mfma_f32_16x16x32_bf16 v[24:27], v[214:217], v[170:173], v[24:27]
	v_mfma_f32_16x16x32_bf16 v[12:15], v[206:209], v[190:193], v[12:15]
	v_mfma_f32_16x16x32_bf16 v[8:11], v[214:217], v[190:193], v[8:11]
	v_mfma_f32_16x16x32_bf16 v[4:7], v[206:209], v[198:201], v[4:7]
	v_mfma_f32_16x16x32_bf16 v[0:3], v[214:217], v[198:201], v[0:3]
	v_add_u32_e32 v154, 0x18000, v139
	s_barrier
	ds_read_b128 v[142:145], v154
	ds_read_b128 v[146:149], v154 offset:1024
	ds_read_b128 v[150:153], v154 offset:2048
	ds_read_b128 v[154:157], v154 offset:3072
	s_add_u32 s16, s16, 0x40000
	s_addc_u32 s17, s17, 0
	s_mov_b32 m0, s23
	ds_read_b128 v[158:161], v141 offset:32768
	ds_read_b128 v[162:165], v141 offset:33792
	ds_read_b128 v[166:169], v141 offset:34816
	ds_read_b128 v[170:173], v141 offset:35840
	ds_read_b128 v[182:185], v141 offset:36864
	ds_read_b128 v[190:193], v141 offset:37888
	ds_read_b128 v[194:197], v141 offset:38912
	ds_read_b128 v[198:201], v141 offset:39936
	global_load_lds_dwordx4 v132, s[16:17]
	s_mov_b32 m0, s26
	s_nop 0
	global_load_lds_dwordx4 v130, s[16:17]
	s_waitcnt lgkmcnt(8)
	s_barrier
	s_waitcnt lgkmcnt(0)
	v_mfma_f32_16x16x32_bf16 v[124:127], v[142:145], v[158:161], v[124:127]
	v_mfma_f32_16x16x32_bf16 v[120:123], v[150:153], v[158:161], v[120:123]
	v_mfma_f32_16x16x32_bf16 v[116:119], v[142:145], v[166:169], v[116:119]
	v_mfma_f32_16x16x32_bf16 v[112:115], v[150:153], v[166:169], v[112:115]
	v_mfma_f32_16x16x32_bf16 v[100:103], v[142:145], v[182:185], v[100:103]
	v_mfma_f32_16x16x32_bf16 v[96:99], v[150:153], v[182:185], v[96:99]
	v_mfma_f32_16x16x32_bf16 v[84:87], v[142:145], v[194:197], v[84:87]
	v_mfma_f32_16x16x32_bf16 v[80:83], v[150:153], v[194:197], v[80:83]
	v_mfma_f32_16x16x32_bf16 v[124:127], v[146:149], v[162:165], v[124:127]
	v_mfma_f32_16x16x32_bf16 v[120:123], v[154:157], v[162:165], v[120:123]
	v_mfma_f32_16x16x32_bf16 v[116:119], v[146:149], v[170:173], v[116:119]
	v_mfma_f32_16x16x32_bf16 v[112:115], v[154:157], v[170:173], v[112:115]
	v_mfma_f32_16x16x32_bf16 v[100:103], v[146:149], v[190:193], v[100:103]
	v_mfma_f32_16x16x32_bf16 v[96:99], v[154:157], v[190:193], v[96:99]
	v_mfma_f32_16x16x32_bf16 v[84:87], v[146:149], v[198:201], v[84:87]
	v_mfma_f32_16x16x32_bf16 v[80:83], v[154:157], v[198:201], v[80:83]
	s_barrier
	v_add_u32_e32 v188, 0x1c000, v139
	s_add_i32 m0, s20, 0x18000
	ds_read_b128 v[202:205], v188
	ds_read_b128 v[206:209], v188 offset:1024
	ds_read_b128 v[210:213], v188 offset:2048
	ds_read_b128 v[214:217], v188 offset:3072
	global_load_lds_dwordx4 v176, s[98:99]
	s_add_i32 m0, s20, 0x1a000
	s_nop 0
	global_load_lds_dwordx4 v128, s[98:99]
	s_barrier
	s_waitcnt lgkmcnt(0)
	v_mfma_f32_16x16x32_bf16 v[108:111], v[202:205], v[158:161], v[108:111]
	v_mfma_f32_16x16x32_bf16 v[104:107], v[210:213], v[158:161], v[104:107]
	v_mfma_f32_16x16x32_bf16 v[92:95], v[202:205], v[166:169], v[92:95]
	v_mfma_f32_16x16x32_bf16 v[88:91], v[210:213], v[166:169], v[88:91]
	v_mfma_f32_16x16x32_bf16 v[76:79], v[202:205], v[182:185], v[76:79]
	v_mfma_f32_16x16x32_bf16 v[72:75], v[210:213], v[182:185], v[72:75]
	v_mfma_f32_16x16x32_bf16 v[68:71], v[202:205], v[194:197], v[68:71]
	v_mfma_f32_16x16x32_bf16 v[64:67], v[210:213], v[194:197], v[64:67]
	v_mfma_f32_16x16x32_bf16 v[108:111], v[206:209], v[162:165], v[108:111]
	v_mfma_f32_16x16x32_bf16 v[104:107], v[214:217], v[162:165], v[104:107]
	v_mfma_f32_16x16x32_bf16 v[92:95], v[206:209], v[170:173], v[92:95]
	v_mfma_f32_16x16x32_bf16 v[88:91], v[214:217], v[170:173], v[88:91]
	v_mfma_f32_16x16x32_bf16 v[76:79], v[206:209], v[190:193], v[76:79]
	v_mfma_f32_16x16x32_bf16 v[72:75], v[214:217], v[190:193], v[72:75]
	v_mfma_f32_16x16x32_bf16 v[68:71], v[206:209], v[198:201], v[68:71]
	v_mfma_f32_16x16x32_bf16 v[64:67], v[214:217], v[198:201], v[64:67]
	s_mov_b32 m0, s28
	s_barrier
	ds_read_b128 v[158:161], v141 offset:49152
	ds_read_b128 v[162:165], v141 offset:50176
	ds_read_b128 v[166:169], v141 offset:51200
	ds_read_b128 v[170:173], v141 offset:52224
	ds_read_b128 v[182:185], v141 offset:53248
	ds_read_b128 v[190:193], v141 offset:54272
	ds_read_b128 v[194:197], v141 offset:55296
	ds_read_b128 v[198:201], v141 offset:56320
	global_load_lds_dwordx4 v132, s[100:101]
	s_mov_b32 m0, s29
	s_nop 0
	global_load_lds_dwordx4 v130, s[100:101]
	s_barrier
	s_waitcnt lgkmcnt(0)
	v_mfma_f32_16x16x32_bf16 v[60:63], v[142:145], v[158:161], v[60:63]
	v_mfma_f32_16x16x32_bf16 v[56:59], v[150:153], v[158:161], v[56:59]
	v_mfma_f32_16x16x32_bf16 v[52:55], v[142:145], v[166:169], v[52:55]
	v_mfma_f32_16x16x32_bf16 v[48:51], v[150:153], v[166:169], v[48:51]
	v_mfma_f32_16x16x32_bf16 v[36:39], v[142:145], v[182:185], v[36:39]
	v_mfma_f32_16x16x32_bf16 v[32:35], v[150:153], v[182:185], v[32:35]
	v_mfma_f32_16x16x32_bf16 v[20:23], v[142:145], v[194:197], v[20:23]
	v_mfma_f32_16x16x32_bf16 v[16:19], v[150:153], v[194:197], v[16:19]
	v_mfma_f32_16x16x32_bf16 v[60:63], v[146:149], v[162:165], v[60:63]
	v_mfma_f32_16x16x32_bf16 v[56:59], v[154:157], v[162:165], v[56:59]
	v_mfma_f32_16x16x32_bf16 v[52:55], v[146:149], v[170:173], v[52:55]
	v_mfma_f32_16x16x32_bf16 v[48:51], v[154:157], v[170:173], v[48:51]
	v_mfma_f32_16x16x32_bf16 v[36:39], v[146:149], v[190:193], v[36:39]
	v_mfma_f32_16x16x32_bf16 v[32:35], v[154:157], v[190:193], v[32:35]
	v_mfma_f32_16x16x32_bf16 v[20:23], v[146:149], v[198:201], v[20:23]
	v_mfma_f32_16x16x32_bf16 v[16:19], v[154:157], v[198:201], v[16:19]
	s_barrier
; __device__ __forceinline__ unsigned cvtpk(float lo, float hi) { const f32x2 v = (f32x2){lo, hi}; const bf16v2 b = __builtin_convertvector(v, bf16v2); return __builtin_bit_cast(unsigned, b); }
; #define PG8_STAGE(bufoff, gbase, voff) do { _Pragma("unroll") for (int _i = 0; _i < 2; ++_i) \
;         __builtin_amdgcn_global_load_lds((const unsigned*)((const char*)(gbase) + (voff)[_i]), (PG8_LAS unsigned*)(lds + (bufoff) + ldsw + _i * 8192), 16, 0, 0); } while (0)
; #define PG8_MMA(ai, bj, At, Bt) do { __builtin_amdgcn_s_setprio(1); _Pragma("unroll") for (int m = 0; m < 4; ++m) _Pragma("unroll") for (int n = 0; n < 2; ++n) _Pragma("unroll") for (int k = 0; k < 2; ++k) \
;         acc[ai][bj][m][n] = __builtin_amdgcn_mfma_f32_16x16x32_bf16(Bt[n][k], At[m][k], acc[ai][bj][m][n], 0, 0, 0); __builtin_amdgcn_s_setprio(0); } while (0)
; #define PG8_WAIT_V(n) asm volatile("s_waitcnt vmcnt(" #n ")" ::: "memory")
; #define PG8_BAR __builtin_amdgcn_s_barrier()
; template <class Epi, class Sched>
; __device__ __forceinline__ void gemm_phase(PG8_LAS unsigned char* lds, const Gemm g, const Sched& S, const Epi& E) {
;     ...
;             PG8_STAGE(PG8_SB(1, 1), b3 + hstep, voffB);
;             PG8_WAIT_V(6); PG8_BAR; PG8_MMA(1, 1, At, B1); PG8_BAR;
;         }
;     __device__ __forceinline__ void operator()(const f32x4 (&acc)[2][2][4][2], const pg8::Unit& u, int wr, int wc, int fr, int fq) const {
;         const int row0 = u.pm * 256 + wr * 64 + fr, col0 = u.pn * 256 + wc * 32 + 8 * fq;
; #pragma unroll
;         for (int ai = 0; ai < 2; ++ai)
; #pragma unroll
;             for (int m = 0; m < 4; ++m) { bf16_t* rowp = O + (size_t)(row0 + ai * 128 + m * 16) * ldc + col0;
; #pragma unroll
;                 for (int bj = 0; bj < 2; ++bj) { const f32x4 v0 = acc[ai][bj][m][0], v1 = acc[ai][bj][m][1];
;                     u32x4 w; w.x = cvtpk(v0[0], v0[1]); w.y = cvtpk(v0[2], v0[3]); w.z = cvtpk(v1[0], v1[1]); w.w = cvtpk(v1[2], v1[3]);
;                     *(u32x4*)(rowp + bj * 128) = w; } }
;     }
	s_add_u32 s14, s14, 0x40080
	s_addc_u32 s15, s15, 0
	s_add_i32 m0, s20, 0x1c000
	s_nop 0
	global_load_lds_dwordx4 v176, s[14:15]
	s_add_i32 m0, s20, 0x1e000
	s_nop 0
	global_load_lds_dwordx4 v128, s[14:15]
	s_waitcnt vmcnt(6)
	s_barrier
	v_mfma_f32_16x16x32_bf16 v[44:47], v[202:205], v[158:161], v[44:47]
	v_mfma_f32_16x16x32_bf16 v[40:43], v[210:213], v[158:161], v[40:43]
	v_mfma_f32_16x16x32_bf16 v[28:31], v[202:205], v[166:169], v[28:31]
	v_mfma_f32_16x16x32_bf16 v[24:27], v[210:213], v[166:169], v[24:27]
	v_mfma_f32_16x16x32_bf16 v[12:15], v[202:205], v[182:185], v[12:15]
	v_mfma_f32_16x16x32_bf16 v[8:11], v[210:213], v[182:185], v[8:11]
	v_mfma_f32_16x16x32_bf16 v[4:7], v[202:205], v[194:197], v[4:7]
	v_mfma_f32_16x16x32_bf16 v[0:3], v[210:213], v[194:197], v[0:3]
	v_mfma_f32_16x16x32_bf16 v[44:47], v[206:209], v[162:165], v[44:47]
	v_mfma_f32_16x16x32_bf16 v[40:43], v[214:217], v[162:165], v[40:43]
	v_mfma_f32_16x16x32_bf16 v[28:31], v[206:209], v[170:173], v[28:31]
	v_mfma_f32_16x16x32_bf16 v[24:27], v[214:217], v[170:173], v[24:27]
	v_mfma_f32_16x16x32_bf16 v[12:15], v[206:209], v[190:193], v[12:15]
	v_mfma_f32_16x16x32_bf16 v[8:11], v[214:217], v[190:193], v[8:11]
	v_mfma_f32_16x16x32_bf16 v[4:7], v[206:209], v[198:201], v[4:7]
	v_mfma_f32_16x16x32_bf16 v[0:3], v[214:217], v[198:201], v[0:3]
	s_add_i32 s45, s45, 2
	s_add_u32 s12, s12, 0x100
	s_addc_u32 s13, s13, 0
	s_add_u32 s43, s43, 0x100
	s_addc_u32 s44, s44, 0
	s_cmp_gt_u32 s45, 13
	s_barrier
	s_cbranch_scc0 .LBB0_358
	v_readlane_b32 s12, v253, 16
	v_lshl_add_u32 v148, s0, 8, v138
	v_lshl_or_b32 v142, s34, 8, v140
	v_readlane_b32 s13, v253, 17
	v_ashrrev_i32_e32 v143, 31, v142
	v_cvt_pk_bf16_f32 v68, v68, v69
	v_mov_b64_e32 v[144:145], s[12:13]
	v_cvt_pk_bf16_f32 v69, v70, v71
	v_cvt_pk_bf16_f32 v70, v64, v65
	v_add_u32_e32 v64, 0x80, v148
	v_mad_i64_i32 v[146:147], s[12:13], v148, s81, v[144:145]
	v_lshlrev_b64 v[142:143], 1, v[142:143]
	v_cvt_pk_bf16_f32 v108, v108, v109
	v_cvt_pk_bf16_f32 v109, v110, v111
	v_cvt_pk_bf16_f32 v110, v104, v105
	v_or_b32_e32 v104, 16, v148
	v_mad_i64_i32 v[64:65], s[12:13], v64, s81, v[144:145]
	v_cvt_pk_bf16_f32 v44, v44, v45
	v_cvt_pk_bf16_f32 v45, v46, v47
	v_cvt_pk_bf16_f32 v46, v40, v41
	v_add_u32_e32 v40, 0x90, v148
	v_lshl_add_u64 v[146:147], v[146:147], 0, v[142:143]
	v_cvt_pk_bf16_f32 v111, v106, v107
	v_mad_i64_i32 v[104:105], s[12:13], v104, s81, v[144:145]
	v_cvt_pk_bf16_f32 v92, v92, v93
	v_cvt_pk_bf16_f32 v93, v94, v95
	v_cvt_pk_bf16_f32 v94, v88, v89
	v_or_b32_e32 v88, 32, v148
	v_lshl_add_u64 v[64:65], v[64:65], 0, v[142:143]
	v_cvt_pk_bf16_f32 v47, v42, v43
	v_mad_i64_i32 v[40:41], s[12:13], v40, s81, v[144:145]
	v_cvt_pk_bf16_f32 v28, v28, v29
	v_cvt_pk_bf16_f32 v29, v30, v31
	v_cvt_pk_bf16_f32 v30, v24, v25
	v_add_u32_e32 v24, 0xa0, v148
	global_store_dwordx4 v[146:147], v[108:111], off offset:256
	v_cvt_pk_bf16_f32 v95, v90, v91
	v_mad_i64_i32 v[88:89], s[12:13], v88, s81, v[144:145]
	v_lshl_add_u64 v[108:109], v[104:105], 0, v[142:143]
	v_cvt_pk_bf16_f32 v76, v76, v77
	v_cvt_pk_bf16_f32 v77, v78, v79
	v_cvt_pk_bf16_f32 v78, v72, v73
	v_or_b32_e32 v72, 48, v148
	global_store_dwordx4 v[64:65], v[44:47], off offset:256
	v_cvt_pk_bf16_f32 v31, v26, v27
	v_mad_i64_i32 v[24:25], s[12:13], v24, s81, v[144:145]
	v_lshl_add_u64 v[44:45], v[40:41], 0, v[142:143]
	v_cvt_pk_bf16_f32 v12, v12, v13
	v_cvt_pk_bf16_f32 v13, v14, v15
	v_cvt_pk_bf16_f32 v14, v8, v9
	v_add_u32_e32 v8, 0xb0, v148
	global_store_dwordx4 v[108:109], v[92:95], off offset:256
	v_cvt_pk_bf16_f32 v79, v74, v75
	v_mad_i64_i32 v[72:73], s[12:13], v72, s81, v[144:145]
	v_lshl_add_u64 v[92:93], v[88:89], 0, v[142:143]
	global_store_dwordx4 v[44:45], v[28:31], off offset:256
	v_cvt_pk_bf16_f32 v15, v10, v11
	v_mad_i64_i32 v[8:9], s[12:13], v8, s81, v[144:145]
	v_lshl_add_u64 v[28:29], v[24:25], 0, v[142:143]
	v_cvt_pk_bf16_f32 v124, v124, v125
	v_cvt_pk_bf16_f32 v125, v126, v127
	v_cvt_pk_bf16_f32 v126, v120, v121
	v_cvt_pk_bf16_f32 v127, v122, v123
	v_cvt_pk_bf16_f32 v104, v116, v117
	v_cvt_pk_bf16_f32 v105, v118, v119
	v_cvt_pk_bf16_f32 v106, v112, v113
	v_cvt_pk_bf16_f32 v107, v114, v115
	v_cvt_pk_bf16_f32 v88, v100, v101
	v_cvt_pk_bf16_f32 v89, v102, v103
	v_cvt_pk_bf16_f32 v90, v96, v97
	v_cvt_pk_bf16_f32 v91, v98, v99
	global_store_dwordx4 v[92:93], v[76:79], off offset:256
	v_cvt_pk_bf16_f32 v74, v80, v81
	v_cvt_pk_bf16_f32 v75, v82, v83
	v_lshl_add_u64 v[76:77], v[72:73], 0, v[142:143]
	v_cvt_pk_bf16_f32 v72, v84, v85
	v_cvt_pk_bf16_f32 v73, v86, v87
	v_cvt_pk_bf16_f32 v71, v66, v67
	v_cvt_pk_bf16_f32 v60, v60, v61
	v_cvt_pk_bf16_f32 v61, v62, v63
	v_cvt_pk_bf16_f32 v62, v56, v57
	v_cvt_pk_bf16_f32 v63, v58, v59
	v_cvt_pk_bf16_f32 v40, v52, v53
	v_cvt_pk_bf16_f32 v41, v54, v55
	v_cvt_pk_bf16_f32 v42, v48, v49
	v_cvt_pk_bf16_f32 v43, v50, v51
	v_cvt_pk_bf16_f32 v24, v36, v37
	v_cvt_pk_bf16_f32 v25, v38, v39
	v_cvt_pk_bf16_f32 v26, v32, v33
	v_cvt_pk_bf16_f32 v27, v34, v35
	global_store_dwordx4 v[28:29], v[12:15], off offset:256
	v_cvt_pk_bf16_f32 v10, v16, v17
	v_cvt_pk_bf16_f32 v11, v18, v19
	v_lshl_add_u64 v[12:13], v[8:9], 0, v[142:143]
	v_cvt_pk_bf16_f32 v8, v20, v21
	v_cvt_pk_bf16_f32 v9, v22, v23
	v_cvt_pk_bf16_f32 v4, v4, v5
	v_cvt_pk_bf16_f32 v5, v6, v7
	v_cvt_pk_bf16_f32 v6, v0, v1
	v_cvt_pk_bf16_f32 v7, v2, v3
	s_and_b64 vcc, exec, s[38:39]
	s_mov_b32 s34, s4
	s_mov_b32 s0, s6
	s_mov_b64 s[14:15], s[10:11]
	s_mov_b64 s[12:13], s[8:9]
	global_store_dwordx4 v[146:147], v[124:127], off
	global_store_dwordx4 v[108:109], v[104:107], off
	global_store_dwordx4 v[92:93], v[88:91], off
	global_store_dwordx4 v[76:77], v[72:75], off
	global_store_dwordx4 v[76:77], v[68:71], off offset:256
	global_store_dwordx4 v[64:65], v[60:63], off
	global_store_dwordx4 v[44:45], v[40:43], off
	global_store_dwordx4 v[28:29], v[24:27], off
	global_store_dwordx4 v[12:13], v[8:11], off
	global_store_dwordx4 v[12:13], v[4:7], off offset:256
	s_cbranch_vccz .LBB0_355
	s_waitcnt vmcnt(0)
	v_readlane_b32 s22, v255, 14
	s_cmpk_gt_u32 s19, 0xff
	v_readlane_b32 s23, v255, 15
	s_mov_b64 s[28:29], s[54:55]
	s_cbranch_scc1 .LBB0_362
	s_barrier
